# hand-written scan loop (2-chunk prefetch, coalesced o stores), FF2 LDS-DMA K-loop, coalesced epilogues FF1/P3b/FF2
# speedup vs baseline: 1.0427x; 1.0427x over previous
; DEV int tidx() { return tidx_full() & 255; }
; DEV int vhalf() { return __builtin_amdgcn_readfirstlane((int)(threadIdx.x >> 8)); }
; DEV void scan_item_mfma(const Params& p, int g, int item, char* smem) {
;   const int L = g ? 8192 : 4096;
;   const int NC = L / 64;
;   const int vs = item & 3, dir = (item >> 2) & 1, h = (item >> 3) & 3, b = item >> 5;
;   char* Qs = smem;
;   char* Ks = Qs + 17408;
;   char* KTs = Ks + 17408;
;   char* Vts = KTs + 18432;
;   char* Ps = Vts + 4608;
;   char* Sts = Ps + 9216;
;   float* decs = (float*)(Sts + 8704);
;   u16* PHG = (u16*)(p.ws + OFF_PHG);
;   const u16* QK = (const u16*)(p.out + (size_t)g * NTOK * D);
;   const u16* Qp = QK + (size_t)(2 * dir) * NTOK * 512;
;   const u16* Kp = Qp + (size_t)NTOK * 512;
;   const u16* KT = (const u16*)(p.ws + OFF_KT);
;   const float* DEC = (const float*)(p.ws + OFF_DEC);
;   const int tid = tidx();
;   const int wave = __builtin_amdgcn_readfirstlane(tid >> 6);
;   const int lane = tid & 63, r = lane & 31, hh = lane >> 5;
;   __syncthreads();
;   for (int e = tid; e < 8704 / 16; e += 256) ((uint4*)Sts)[e] = make_uint4(0, 0, 0, 0);
;   f32x16 accS[2];
; #pragma unroll
;   for (int t = 0; t < 2; ++t)
; #pragma unroll
;     for (int i = 0; i < 16; ++i) accS[t][i] = 0.f;
;   const int ocol = (dir ? 1024 : 0) + h * 128 + vs * 32;
;   uint4 q0, q1, q2, q3, k0, k1, k2, k3, t0, t1, t2, t3, vv;
;   float dd = 0.f;
;   const int qrow = tid >> 4, qc = tid & 15;
;   const int trow = tid >> 3, tc = tid & 7;
;   const int vrow = tid >> 2, vc = tid & 3;
; DEV void phase_p2_naive(const Params& p, int g, char* hsm) {
;   __shared__ int s_item;
;   const int nscan = g ? 128 : 256;
;   const int nhy = 1024;
;   unsigned* cnt = (unsigned*)(p.ws + OFF_CNT) + g;
;   const int half = vhalf();
;   if ((int)blockIdx.x * 2 < nscan) scan_item_mfma(p, g, blockIdx.x * 2 + half, hsm);
.LBB0_667:
	s_movk_i32 s40, 0x1400
	s_or_b64 exec, exec, s[0:1]
	s_and_b64 s[0:1], s[66:67], exec
	v_readfirstlane_b32 s24, v202
	s_cselect_b32 s0, 0x100, s61
	s_lshr_b32 s26, s24, 8
	s_cmp_ge_i32 s81, s0
	s_waitcnt lgkmcnt(0)
	s_barrier
	s_cbranch_scc1 .LBB0_720
	v_writelane_b32 v160, s0, 0
	v_writelane_b32 v160, s1, 1
	v_writelane_b32 v160, s2, 2
	v_writelane_b32 v160, s3, 3
	v_writelane_b32 v160, s4, 4
	v_writelane_b32 v160, s5, 5
	v_writelane_b32 v160, s6, 6
	v_writelane_b32 v160, s7, 7
	v_writelane_b32 v160, s8, 8
	v_writelane_b32 v160, s9, 9
	v_writelane_b32 v160, s10, 10
	v_writelane_b32 v160, s11, 11
	v_writelane_b32 v160, s12, 12
	v_writelane_b32 v160, s13, 13
	v_writelane_b32 v160, s14, 14
	v_writelane_b32 v160, s15, 15
	v_writelane_b32 v160, s16, 16
	v_writelane_b32 v160, s17, 17
	v_writelane_b32 v160, s18, 18
	v_writelane_b32 v160, s19, 19
	v_writelane_b32 v160, s20, 20
	v_writelane_b32 v160, s21, 21
	v_writelane_b32 v160, s22, 22
	v_writelane_b32 v160, s23, 23
	v_writelane_b32 v160, s24, 24
	v_writelane_b32 v160, s25, 25
	v_writelane_b32 v160, s26, 26
	v_writelane_b32 v160, s27, 27
	v_writelane_b32 v160, s28, 28
	v_writelane_b32 v160, s29, 29
	v_writelane_b32 v160, s30, 30
	v_writelane_b32 v160, s31, 31
	v_writelane_b32 v160, s33, 33
	v_writelane_b32 v160, s34, 34
	v_writelane_b32 v160, s35, 35
	v_writelane_b32 v160, s36, 36
	v_writelane_b32 v160, s37, 37
	v_writelane_b32 v160, s38, 38
	v_writelane_b32 v160, s39, 39
	v_writelane_b32 v160, s40, 40
	v_writelane_b32 v160, s41, 41
	v_writelane_b32 v160, s42, 42
	v_writelane_b32 v160, s43, 43
	v_writelane_b32 v160, s44, 44
	v_writelane_b32 v160, s45, 45
	v_writelane_b32 v160, s46, 46
	v_writelane_b32 v160, s47, 47
	v_writelane_b32 v160, s48, 48
	v_writelane_b32 v160, s49, 49
	v_writelane_b32 v160, s50, 50
	v_writelane_b32 v160, s51, 51
	v_writelane_b32 v160, s52, 52
	v_writelane_b32 v160, s53, 53
	v_writelane_b32 v160, s54, 54
	v_writelane_b32 v160, s55, 55
	v_writelane_b32 v160, s56, 56
	v_writelane_b32 v160, s57, 57
	v_writelane_b32 v160, s58, 58
	v_writelane_b32 v160, s59, 59
	v_writelane_b32 v160, s60, 60
	v_writelane_b32 v160, s61, 61
	v_writelane_b32 v160, s62, 62
	v_writelane_b32 v160, s63, 63
	v_writelane_b32 v161, s64, 0
	v_writelane_b32 v161, s65, 1
	v_writelane_b32 v161, s66, 2
	v_writelane_b32 v161, s67, 3
	v_writelane_b32 v161, s68, 4
	v_writelane_b32 v161, s69, 5
	v_writelane_b32 v161, s70, 6
	v_writelane_b32 v161, s71, 7
	v_writelane_b32 v161, s72, 8
	v_writelane_b32 v161, s73, 9
	s_barrier
	s_add_i32 s2, s26, s81
	s_and_b32 s3, s2, 3
	s_bfe_u32 s4, s2, 0x10002
	s_bfe_u32 s5, s2, 0x20003
	s_lshr_b32 s6, s2, 5
	s_and_b64 s[0:1], s[66:67], exec
	s_cselect_b32 s7, 64, 0x80
	s_bfe_u32 s9, s24, 0x20006
	v_and_b32_e32 v53, 0xff, v202
	v_and_b32_e32 v54, 63, v202
	v_and_b32_e32 v55, 31, v202
	v_bfe_u32 v109, v202, 5, 1
	v_bfe_u32 v110, v202, 6, 2
	v_lshrrev_b32_e32 v220, 4, v53
	v_and_b32_e32 v221, 15, v53
	v_lshlrev_b32_e32 v219, 4, v221
	v_lshl_add_u32 v209, v220, 10, v219
	v_add_u32_e32 v210, 0x4000, v209
	v_add_u32_e32 v211, 0x8000, v209
	v_add_u32_e32 v212, 0xc000, v209
	v_mul_u32_u24_e32 v248, 0x110, v220
	v_add3_u32 v234, v248, v219, s92
	v_lshrrev_b32_e32 v220, 3, v53
	v_and_b32_e32 v221, 7, v53
	v_lshlrev_b32_e32 v219, 4, v221
	v_lshl_add_u32 v213, v220, 7, v219
	v_add_u32_e32 v214, 0x3000, v213
	v_add_u32_e32 v213, 0x1000, v213
	v_mul_u32_u24_e32 v248, 0x90, v220
	v_add3_u32 v235, v248, v219, s92
	v_lshrrev_b32_e32 v220, 2, v53
	v_and_b32_e32 v221, 3, v53
	v_mul_u32_u24_e32 v219, 0x1400, v220
	v_lshl_add_u32 v215, v221, 4, v219
	v_mul_u32_u24_e32 v219, 0x480, v221
	v_lshl_add_u32 v219, v220, 1, v219
	v_add_u32_e32 v236, s92, v219
	v_and_b32_e32 v220, 0x7f, v53
	v_lshlrev_b32_e32 v216, 2, v220
	v_add_u32_e32 v237, s92, v216
	v_add_u32_e32 v237, 0x10000, v237
	v_mul_u32_u24_e32 v220, 0x110, v55
	v_mul_u32_u24_e32 v221, 0x90, v55
	v_lshlrev_b32_e32 v219, 4, v109
	v_add3_u32 v245, v220, v219, s92
	v_add3_u32 v244, v221, v219, s92
	v_lshrrev_b32_e32 v248, 1, v110
	v_mul_u32_u24_e32 v248, 0x2200, v248
	v_add_u32_e32 v240, v245, v248
	v_and_b32_e32 v248, 1, v110
	v_mul_u32_u24_e32 v248, 0x2200, v248
	v_add_u32_e32 v242, v245, v248
	v_mul_u32_u24_e32 v248, 0x2200, v110
	v_add_u32_e32 v241, v245, v248
	v_mul_u32_u24_e32 v248, 0x1200, v110
	v_add_u32_e32 v243, v244, v248
	v_lshrrev_b32_e32 v248, 1, v110
	v_mul_u32_u24_e32 v248, 0x1200, v248
	v_add3_u32 v239, v221, v248, s92
	v_and_b32_e32 v248, 1, v110
	v_lshlrev_b32_e32 v248, 6, v248
	v_lshl_add_u32 v248, v109, 3, v248
	v_add_u32_e32 v239, v239, v248
	v_subrev_u32_e32 v248, 2, v110
	v_lshlrev_b32_e32 v219, 7, v248
	v_lshl_add_u32 v219, v109, 3, v219
	v_add3_u32 v238, v220, v219, s92
	v_add_u32_e32 v238, 0x10000, v238
	v_add_u32_e32 v164, 0x10000, v245
	v_mul_u32_u24_e32 v219, 0x2400, v248
	v_add_u32_e32 v207, v244, v219
	v_lshlrev_b32_e32 v219, 8, v248
	v_lshl_add_u32 v219, v109, 4, v219
	v_add_u32_e32 v208, s92, v219
	v_add_u32_e32 v208, 0x10000, v208
	v_lshl_add_u32 v219, v110, 5, v55
	v_mul_u32_u24_e32 v219, 0x1400, v219
	v_lshl_add_u32 v217, v109, 3, v219
	v_lshlrev_b32_e32 v219, 2, v109
	v_sub_u32_e32 v218, v55, v219
	s_cmp_eq_u32 s4, 0
	s_cbranch_scc0 .Lscan_d1
; DEV void scan_item_mfma(const Params& p, int g, int item, char* smem) {
;     ...
;   for (int e = tid; e < 8704 / 16; e += 256) ((uint4*)Sts)[e] = make_uint4(0, 0, 0, 0);
;   f32x16 accS[2];
; #pragma unroll
;   for (int t = 0; t < 2; ++t)
; #pragma unroll
;     for (int i = 0; i < 16; ++i) accS[t][i] = 0.f;
;   const int ocol = (dir ? 1024 : 0) + h * 128 + vs * 32;
;   uint4 q0, q1, q2, q3, k0, k1, k2, k3, t0, t1, t2, t3, vv;
;   float dd = 0.f;
;   const int qrow = tid >> 4, qc = tid & 15;
;   const int trow = tid >> 3, tc = tid & 7;
;   const int vrow = tid >> 2, vc = tid & 3;
;     ...
;   unsigned opk[8] = {0u, 0u, 0u, 0u, 0u, 0u, 0u, 0u};
;   size_t otok = 0;
;   SCAN_ISSUE(dir ? NC - 1 : 0);
	s_mul_i32 s11, s6, s7
	s_mov_b32 s12, s64
	s_mov_b32 s13, s65
	s_mul_i32 s0, s11, 0x10000
	s_add_u32 s12, s12, s0
	s_addc_u32 s13, s13, 0
	s_mul_i32 s0, s5, 0x100
	s_add_u32 s12, s12, s0
	s_addc_u32 s13, s13, 0
	s_add_u32 s14, s12, 0x2000000
	s_addc_u32 s15, s13, 0
	s_add_u32 s16, s88, 0x3d4c100
	s_addc_u32 s17, s89, 0
	s_mul_i32 s0, s11, 0x20000
	s_add_u32 s16, s16, s0
	s_addc_u32 s17, s17, 0
	s_mul_i32 s0, s5, 0x4000
	s_add_u32 s16, s16, s0
	s_addc_u32 s17, s17, 0
	s_add_u32 s18, s88, 0xdd4c500
	s_addc_u32 s19, s89, 0
	s_mul_i32 s0, s11, 0x50000
	s_add_u32 s18, s18, s0
	s_addc_u32 s19, s19, 0
	s_mul_i32 s0, s5, 0x100
	s_add_u32 s18, s18, s0
	s_addc_u32 s19, s19, 0
	s_mul_i32 s0, s3, 0x40
	s_add_u32 s18, s18, s0
	s_addc_u32 s19, s19, 0
	s_add_u32 s20, s88, 0x3b4c100
	s_addc_u32 s21, s89, 0
	s_mul_i32 s0, s11, 0x800
	s_add_u32 s20, s20, s0
	s_addc_u32 s21, s21, 0
	s_mul_i32 s0, s5, 0x200
	s_add_u32 s20, s20, s0
	s_addc_u32 s21, s21, 0
	s_add_u32 s22, s88, 0xdd4c100
	s_addc_u32 s23, s89, 0
	s_mul_i32 s0, s11, 0x50000
	s_add_u32 s22, s22, s0
	s_addc_u32 s23, s23, 0
	s_mul_i32 s0, s5, 0x100
	s_add_u32 s22, s22, s0
	s_addc_u32 s23, s23, 0
	s_mul_i32 s0, s3, 0x40
	s_add_u32 s22, s22, s0
	s_addc_u32 s23, s23, 0
	v_cmp_le_i32_e64 s[34:35], 0, v218
	v_cmp_le_i32_e64 s[36:37], 1, v218
	v_cmp_le_i32_e64 s[38:39], 2, v218
	v_cmp_le_i32_e64 s[40:41], 3, v218
	v_cmp_le_i32_e64 s[42:43], 8, v218
	v_cmp_le_i32_e64 s[44:45], 9, v218
	v_cmp_le_i32_e64 s[46:47], 10, v218
	v_cmp_le_i32_e64 s[48:49], 11, v218
	v_cmp_le_i32_e64 s[50:51], 16, v218
	v_cmp_le_i32_e64 s[52:53], 17, v218
	v_cmp_le_i32_e64 s[54:55], 18, v218
	v_cmp_le_i32_e64 s[56:57], 19, v218
	v_cmp_le_i32_e64 s[58:59], 24, v218
	v_cmp_le_i32_e64 s[60:61], 25, v218
	v_cmp_le_i32_e64 s[62:63], 26, v218
	v_cmp_le_i32_e64 s[64:65], 27, v218
	v_mov_b32_e32 v144, 0
	v_mov_b32_e32 v145, 0
	v_mov_b32_e32 v146, 0
	v_mov_b32_e32 v147, 0
	v_mov_b64_e32 v[112:113], v[144:145]
	v_mov_b64_e32 v[114:115], v[144:145]
	v_mov_b64_e32 v[116:117], v[144:145]
	v_mov_b64_e32 v[118:119], v[144:145]
	v_mov_b64_e32 v[120:121], v[144:145]
	v_mov_b64_e32 v[122:123], v[144:145]
	v_mov_b64_e32 v[124:125], v[144:145]
	v_mov_b64_e32 v[126:127], v[144:145]
	v_mov_b64_e32 v[128:129], v[144:145]
	v_mov_b64_e32 v[130:131], v[144:145]
	v_mov_b64_e32 v[132:133], v[144:145]
	v_mov_b64_e32 v[134:135], v[144:145]
	v_mov_b64_e32 v[136:137], v[144:145]
	v_mov_b64_e32 v[138:139], v[144:145]
	v_mov_b64_e32 v[140:141], v[144:145]
	v_mov_b64_e32 v[142:143], v[144:145]
	v_lshl_add_u32 v220, v53, 5, s92
	v_add_u32_e32 v220, 0x10000, v220
	ds_write_b128 v220, v[144:147] offset:1536
	ds_write_b128 v220, v[144:147] offset:1552
	v_and_b32_e32 v221, 31, v53
	v_lshl_add_u32 v221, v221, 4, s92
	v_add_u32_e32 v221, 0x10000, v221
	ds_write_b128 v221, v[144:147] offset:9728
	s_cmp_eq_u32 s9, 1
	s_cbranch_scc0 .Lsc0_nz
	v_mul_u32_u24_e32 v219, 24, v109
	v_add_u32_e32 v219, v239, v219
	ds_write_b128 v219, v[144:147] offset:57856
	ds_write_b128 v219, v[144:147] offset:57872
.Lsc0_nz:
	global_load_dwordx4 v[0:3], v209, s[12:13]
	global_load_dwordx4 v[4:7], v210, s[12:13]
	global_load_dwordx4 v[8:11], v211, s[12:13]
	global_load_dwordx4 v[12:15], v212, s[12:13]
	global_load_dwordx4 v[16:19], v209, s[14:15]
	global_load_dwordx4 v[20:23], v210, s[14:15]
	global_load_dwordx4 v[24:27], v211, s[14:15]
	global_load_dwordx4 v[28:31], v212, s[14:15]
	global_load_dwordx4 v[32:35], v213, s[16:17] offset:-4096
	global_load_dwordx4 v[36:39], v213, s[16:17]
	global_load_dwordx4 v[40:43], v214, s[16:17] offset:-4096
	global_load_dwordx4 v[44:47], v214, s[16:17]
	global_load_dwordx4 v[48:51], v215, s[18:19]
	global_load_dword v52, v216, s[20:21]
	s_sub_i32 s10, s7, 1
	s_cmp_gt_i32 s10, 0
	s_cselect_b32 s1, 1, 0
	s_sub_i32 s10, s10, s1
	s_mul_i32 s0, s1, 0x10000
	s_add_u32 s12, s12, s0
	s_addc_u32 s13, s13, 0
	s_mul_i32 s0, s1, 0x10000
	s_add_u32 s14, s14, s0
	s_addc_u32 s15, s15, 0
	s_mul_i32 s0, s1, 0x20000
	s_add_u32 s16, s16, s0
	s_addc_u32 s17, s17, 0
	s_mul_i32 s0, s1, 0x50000
	s_add_u32 s18, s18, s0
	s_addc_u32 s19, s19, 0
	s_mul_i32 s0, s1, 0x800
	s_add_u32 s20, s20, s0
	s_addc_u32 s21, s21, 0
	global_load_dwordx4 v[56:59], v209, s[12:13]
	global_load_dwordx4 v[60:63], v210, s[12:13]
	global_load_dwordx4 v[64:67], v211, s[12:13]
	global_load_dwordx4 v[68:71], v212, s[12:13]
	global_load_dwordx4 v[72:75], v209, s[14:15]
	global_load_dwordx4 v[76:79], v210, s[14:15]
	global_load_dwordx4 v[80:83], v211, s[14:15]
	global_load_dwordx4 v[84:87], v212, s[14:15]
	global_load_dwordx4 v[88:91], v213, s[16:17] offset:-4096
	global_load_dwordx4 v[92:95], v213, s[16:17]
	global_load_dwordx4 v[96:99], v214, s[16:17] offset:-4096
	global_load_dwordx4 v[100:103], v214, s[16:17]
	global_load_dwordx4 v[104:107], v215, s[18:19]
	global_load_dword v108, v216, s[20:21]
	s_cmp_lt_u32 s9, 2
	s_cbranch_scc0 .Lsc0_w1sfa
	s_waitcnt vmcnt(14)
	s_branch .Lsc0_w1efa
.Lsc0_w1sfa:
	s_waitcnt vmcnt(14)
; DEV void scan_item_mfma(const Params& p, int g, int item, char* smem) {
;     ...
;     {
;       char* d = Qs + qrow * 272 + qc * 16;
;       *(uint4*)(d) = q0; *(uint4*)(d + 16 * 272) = q1; *(uint4*)(d + 32 * 272) = q2; *(uint4*)(d + 48 * 272) = q3;
;       d = Ks + qrow * 272 + qc * 16;
;       *(uint4*)(d) = k0; *(uint4*)(d + 16 * 272) = k1; *(uint4*)(d + 32 * 272) = k2; *(uint4*)(d + 48 * 272) = k3;
;       d = KTs + trow * 144 + tc * 16;
;       *(uint4*)(d) = t0; *(uint4*)(d + 32 * 144) = t1; *(uint4*)(d + 64 * 144) = t2; *(uint4*)(d + 96 * 144) = t3;
;       st8t(Vts + (vc * 8) * 144 + vrow * 2, vv);
;       if (tid < 128) decs[tid] = dd;
;       if (wave < 2 && ci > 0) {
;         u16* og = PHG + (otok + 32 * wave + 4 * hh) * 2560 + ocol + r;
; #pragma unroll
;         for (int i = 0; i < 8; ++i) {
;           og[(size_t)(((2 * i) & 3) + 8 * ((2 * i) >> 2)) * 2560] = (u16)(opk[i] & 0xffffu);
;           og[(size_t)(((2 * i + 1) & 3) + 8 * ((2 * i + 1) >> 2)) * 2560] = (u16)(opk[i] >> 16);
;         }
;       }
;       if (wave >= 2 && ci > 0) {
; #pragma unroll
;         for (int t = 0; t < 2; ++t) {
;           const int kt = 2 * (wave - 2) + t;
; #pragma unroll
;           for (int rg = 0; rg < 4; ++rg) {
;             const int kk0 = 32 * kt + 8 * rg + 4 * hh;
;             *(uint2*)(Sts + r * 272 + kk0 * 2) = make_uint2(pack2(accS[t][4 * rg + 0], accS[t][4 * rg + 1]),
;                                                             pack2(accS[t][4 * rg + 2], accS[t][4 * rg + 3]));
;           }
;         }
;       }
;     }
;     SCAN_BAR();
;     {
;       const int nn = (ci + 1 < NC) ? (dir ? NC - 2 - ci : ci + 1) : n;
;       SCAN_ISSUE(nn);
;     }
;     __builtin_amdgcn_sched_barrier(0);
;     {
;       const int jt = wave >> 1, st = wave & 1;
;       const bool active = dir ? (st >= jt) : (st <= jt);
;       f32x16 pa;
; #pragma unroll
;       for (int i = 0; i < 16; ++i) pa[i] = 0.f;
;       if (active) {
;         bf16x8 qa[8], kb[8];
; #pragma unroll
;         for (int ks = 0; ks < 8; ++ks) {
;           qa[ks] = *(const bf16x8*)(Qs + (32 * jt + r) * 272 + ks * 32 + hh * 16);
;           kb[ks] = *(const bf16x8*)(Ks + (32 * st + r) * 272 + ks * 32 + hh * 16);
;         }
;         __builtin_amdgcn_sched_barrier(0);
;         f32x16 p1;
; #pragma unroll
;         for (int i = 0; i < 16; ++i) p1[i] = 0.f;
; #pragma unroll
.Lsc0_w1efa:
	ds_write_b128 v234, v[0:3] offset:0
	ds_write_b128 v234, v[4:7] offset:4352
	ds_write_b128 v234, v[8:11] offset:8704
	ds_write_b128 v234, v[12:15] offset:13056
	ds_write_b128 v234, v[16:19] offset:17408
	ds_write_b128 v234, v[20:23] offset:21760
	ds_write_b128 v234, v[24:27] offset:26112
	ds_write_b128 v234, v[28:31] offset:30464
	ds_write_b128 v235, v[32:35] offset:34816
	ds_write_b128 v235, v[36:39] offset:39424
	ds_write_b128 v235, v[40:43] offset:44032
	ds_write_b128 v235, v[44:47] offset:48640
	ds_write_b16 v236, v48 offset:53248
	ds_write_b16_d16_hi v236, v48 offset:53392
	ds_write_b16 v236, v49 offset:53536
	ds_write_b16_d16_hi v236, v49 offset:53680
	ds_write_b16 v236, v50 offset:53824
	ds_write_b16_d16_hi v236, v50 offset:53968
	ds_write_b16 v236, v51 offset:54112
	ds_write_b16_d16_hi v236, v51 offset:54256
	ds_write_b32 v237, v52 offset:10240
	s_cmp_lt_u32 s9, 2
	s_cbranch_scc1 .Lsc0_p1ofa
	v_cvt_pk_bf16_f32 v166, v112, v113
	v_cvt_pk_bf16_f32 v167, v114, v115
	ds_write_b64 v238, v[166:167] offset:1536
	v_cvt_pk_bf16_f32 v168, v116, v117
	v_cvt_pk_bf16_f32 v169, v118, v119
	ds_write_b64 v238, v[168:169] offset:1552
	v_cvt_pk_bf16_f32 v170, v120, v121
	v_cvt_pk_bf16_f32 v171, v122, v123
	ds_write_b64 v238, v[170:171] offset:1568
	v_cvt_pk_bf16_f32 v172, v124, v125
	v_cvt_pk_bf16_f32 v173, v126, v127
	ds_write_b64 v238, v[172:173] offset:1584
	v_cvt_pk_bf16_f32 v174, v128, v129
	v_cvt_pk_bf16_f32 v175, v130, v131
	ds_write_b64 v238, v[174:175] offset:1600
	v_cvt_pk_bf16_f32 v176, v132, v133
	v_cvt_pk_bf16_f32 v177, v134, v135
	ds_write_b64 v238, v[176:177] offset:1616
	v_cvt_pk_bf16_f32 v178, v136, v137
	v_cvt_pk_bf16_f32 v179, v138, v139
	ds_write_b64 v238, v[178:179] offset:1632
	v_cvt_pk_bf16_f32 v180, v140, v141
	v_cvt_pk_bf16_f32 v181, v142, v143
	ds_write_b64 v238, v[180:181] offset:1648
.Lsc0_p1ofa:
	s_waitcnt lgkmcnt(0)
	s_barrier
	s_cmp_gt_i32 s10, 0
	s_cselect_b32 s1, 1, 0
	s_sub_i32 s10, s10, s1
	s_mul_i32 s0, s1, 0x10000
	s_add_u32 s12, s12, s0
	s_addc_u32 s13, s13, 0
	s_mul_i32 s0, s1, 0x10000
	s_add_u32 s14, s14, s0
	s_addc_u32 s15, s15, 0
	s_mul_i32 s0, s1, 0x20000
	s_add_u32 s16, s16, s0
	s_addc_u32 s17, s17, 0
	s_mul_i32 s0, s1, 0x50000
	s_add_u32 s18, s18, s0
	s_addc_u32 s19, s19, 0
	s_mul_i32 s0, s1, 0x800
	s_add_u32 s20, s20, s0
	s_addc_u32 s21, s21, 0
	global_load_dwordx4 v[0:3], v209, s[12:13]
	global_load_dwordx4 v[4:7], v210, s[12:13]
	global_load_dwordx4 v[8:11], v211, s[12:13]
	global_load_dwordx4 v[12:15], v212, s[12:13]
	global_load_dwordx4 v[16:19], v209, s[14:15]
	global_load_dwordx4 v[20:23], v210, s[14:15]
	global_load_dwordx4 v[24:27], v211, s[14:15]
	global_load_dwordx4 v[28:31], v212, s[14:15]
	global_load_dwordx4 v[32:35], v213, s[16:17] offset:-4096
	global_load_dwordx4 v[36:39], v213, s[16:17]
	global_load_dwordx4 v[40:43], v214, s[16:17] offset:-4096
	global_load_dwordx4 v[44:47], v214, s[16:17]
	global_load_dwordx4 v[48:51], v215, s[18:19]
	global_load_dword v52, v216, s[20:21]
	s_cmp_eq_u32 s9, 1
	s_cbranch_scc1 .Lsc0_p2efa
	ds_read_b128 v[166:169], v240
	ds_read_b128 v[170:173], v240 offset:32
	ds_read_b128 v[174:177], v240 offset:64
	ds_read_b128 v[178:181], v240 offset:96
	ds_read_b128 v[182:185], v242 offset:17408
	ds_read_b128 v[186:189], v242 offset:17440
	ds_read_b128 v[190:193], v242 offset:17472
	ds_read_b128 v[194:197], v242 offset:17504
	s_waitcnt lgkmcnt(0)
	v_mfma_f32_32x32x16_bf16 v[144:159], v[182:185], v[166:169], 0
	v_mfma_f32_32x32x16_bf16 v[144:159], v[186:189], v[170:173], v[144:159]
	v_mfma_f32_32x32x16_bf16 v[144:159], v[190:193], v[174:177], v[144:159]
	v_mfma_f32_32x32x16_bf16 v[144:159], v[194:197], v[178:181], v[144:159]
	ds_read_b128 v[166:169], v240 offset:128
	ds_read_b128 v[170:173], v240 offset:160
	ds_read_b128 v[174:177], v240 offset:192
	ds_read_b128 v[178:181], v240 offset:224
	ds_read_b128 v[182:185], v242 offset:17536
	ds_read_b128 v[186:189], v242 offset:17568
	ds_read_b128 v[190:193], v242 offset:17600
	ds_read_b128 v[194:197], v242 offset:17632
	s_waitcnt lgkmcnt(0)
	v_mfma_f32_32x32x16_bf16 v[144:159], v[182:185], v[166:169], v[144:159]
	v_mfma_f32_32x32x16_bf16 v[144:159], v[186:189], v[170:173], v[144:159]
	v_mfma_f32_32x32x16_bf16 v[144:159], v[190:193], v[174:177], v[144:159]
	v_mfma_f32_32x32x16_bf16 v[144:159], v[194:197], v[178:181], v[144:159]
	s_nop 7
	s_nop 7
	s_cmp_eq_u32 s9, 0
	s_cbranch_scc1 .Lsc0_p2mfa
	s_cmp_eq_u32 s9, 3
	s_cbranch_scc0 .Lsc0_p2nfa
.Lsc0_p2mfa:
	v_cndmask_b32_e64 v144, 0, v144, s[34:35]
	v_cndmask_b32_e64 v145, 0, v145, s[36:37]
	v_cndmask_b32_e64 v146, 0, v146, s[38:39]
	v_cndmask_b32_e64 v147, 0, v147, s[40:41]
	v_cndmask_b32_e64 v148, 0, v148, s[42:43]
	v_cndmask_b32_e64 v149, 0, v149, s[44:45]
	v_cndmask_b32_e64 v150, 0, v150, s[46:47]
	v_cndmask_b32_e64 v151, 0, v151, s[48:49]
	v_cndmask_b32_e64 v152, 0, v152, s[50:51]
	v_cndmask_b32_e64 v153, 0, v153, s[52:53]
	v_cndmask_b32_e64 v154, 0, v154, s[54:55]
	v_cndmask_b32_e64 v155, 0, v155, s[56:57]
	v_cndmask_b32_e64 v156, 0, v156, s[58:59]
	v_cndmask_b32_e64 v157, 0, v157, s[60:61]
	v_cndmask_b32_e64 v158, 0, v158, s[62:63]
	v_cndmask_b32_e64 v159, 0, v159, s[64:65]
.Lsc0_p2nfa:
	v_cvt_pk_bf16_f32 v144, v144, v145
	v_cvt_pk_bf16_f32 v145, v146, v147
	ds_write_b64 v239, v[144:145] offset:57856
	v_cvt_pk_bf16_f32 v148, v148, v149
	v_cvt_pk_bf16_f32 v149, v150, v151
	ds_write_b64 v239, v[148:149] offset:57872
	v_cvt_pk_bf16_f32 v152, v152, v153
	v_cvt_pk_bf16_f32 v153, v154, v155
	ds_write_b64 v239, v[152:153] offset:57888
	v_cvt_pk_bf16_f32 v156, v156, v157
	v_cvt_pk_bf16_f32 v157, v158, v159
	ds_write_b64 v239, v[156:157] offset:57904
; DEV void scan_item_mfma(const Params& p, int g, int item, char* smem) {
;     ...
;     SCAN_BAR();
;     if (wave < 2) {
;       const int jt = wave;
;       bf16x8 pp[4], vb[4], qa[4], sb[4];
; #pragma unroll
;       for (int ks = 0; ks < 4; ++ks) {
;         pp[ks] = *(const bf16x8*)(Ps + (32 * jt + r) * 144 + ks * 32 + hh * 16);
;         vb[ks] = *(const bf16x8*)(Vts + r * 144 + ks * 32 + hh * 16);
;         qa[ks] = *(const bf16x8*)(Qs + (32 * jt + r) * 272 + ks * 32 + hh * 16);
;         sb[ks] = *(const bf16x8*)(Sts + r * 272 + ks * 32 + hh * 16);
;       }
;       __builtin_amdgcn_sched_barrier(0);
;       f32x16 o, o1;
; #pragma unroll
;       for (int i = 0; i < 16; ++i) { o[i] = 0.f; o1[i] = 0.f; }
; #pragma unroll
;       for (int ks = 0; ks < 4; ++ks) {
;         o = __builtin_amdgcn_mfma_f32_32x32x16_bf16(pp[ks], vb[ks], o, 0, 0, 0);
;         o1 = __builtin_amdgcn_mfma_f32_32x32x16_bf16(qa[ks], sb[ks], o1, 0, 0, 0);
;       }
;       __builtin_amdgcn_sched_barrier(0);
; #pragma unroll
;       for (int ks = 0; ks < 4; ++ks) {
;         qa[ks] = *(const bf16x8*)(Qs + (32 * jt + r) * 272 + (ks + 4) * 32 + hh * 16);
;         sb[ks] = *(const bf16x8*)(Sts + r * 272 + (ks + 4) * 32 + hh * 16);
;       }
;       __builtin_amdgcn_sched_barrier(0);
;       o = __builtin_amdgcn_mfma_f32_32x32x16_bf16(qa[0], sb[0], o, 0, 0, 0);
;       o1 = __builtin_amdgcn_mfma_f32_32x32x16_bf16(qa[1], sb[1], o1, 0, 0, 0);
;       o = __builtin_amdgcn_mfma_f32_32x32x16_bf16(qa[2], sb[2], o, 0, 0, 0);
;       o1 = __builtin_amdgcn_mfma_f32_32x32x16_bf16(qa[3], sb[3], o1, 0, 0, 0);
;       f32x16 o2;
; #pragma unroll
;       for (int i = 0; i < 16; ++i) o2[i] = 0.f;
; #pragma unroll
;       for (int i = 0; i < 8; ++i)
;         opk[i] = pack2(o[2 * i] + o1[2 * i] + o2[2 * i], o[2 * i + 1] + o1[2 * i + 1] + o2[2 * i + 1]);
;       otok = tok0;
;     } else {
;       const int kt0 = 2 * (wave - 2);
;       bf16x8 ka[2][4], vb[4];
; #pragma unroll
;       for (int ks = 0; ks < 4; ++ks) {
;         vb[ks] = *(const bf16x8*)(Vts + r * 144 + ks * 32 + hh * 16);
;         ka[0][ks] = *(const bf16x8*)(KTs + (32 * kt0 + r) * 144 + ks * 32 + hh * 16);
;         ka[1][ks] = *(const bf16x8*)(KTs + (32 * (kt0 + 1) + r) * 144 + ks * 32 + hh * 16);
;       }
;       __builtin_amdgcn_sched_barrier(0);
; #pragma unroll
;       for (int ks = 0; ks < 4; ++ks) {
.Lsc0_p2efa:
	s_waitcnt lgkmcnt(0)
	s_barrier
	s_cmp_lt_u32 s9, 2
	s_cbranch_scc0 .Lsc0_p3sfa
	ds_read_b128 v[166:169], v243 offset:57856
	ds_read_b128 v[170:173], v243 offset:57888
	ds_read_b128 v[174:177], v243 offset:57920
	ds_read_b128 v[178:181], v243 offset:57952
	ds_read_b128 v[182:185], v244 offset:53248
	ds_read_b128 v[186:189], v244 offset:53280
	ds_read_b128 v[190:193], v244 offset:53312
	ds_read_b128 v[194:197], v244 offset:53344
	ds_read_b128 v[198:201], v241
	ds_read_b128 v[222:225], v241 offset:32
	ds_read_b128 v[226:229], v241 offset:64
	ds_read_b128 v[230:233], v241 offset:96
	s_waitcnt lgkmcnt(4)
	v_mfma_f32_32x32x16_bf16 v[112:127], v[182:185], v[166:169], 0
	v_mfma_f32_32x32x16_bf16 v[112:127], v[186:189], v[170:173], v[112:127]
	v_mfma_f32_32x32x16_bf16 v[112:127], v[190:193], v[174:177], v[112:127]
	v_mfma_f32_32x32x16_bf16 v[112:127], v[194:197], v[178:181], v[112:127]
	ds_read_b128 v[166:169], v164 offset:1536
	ds_read_b128 v[170:173], v164 offset:1568
	ds_read_b128 v[174:177], v164 offset:1600
	ds_read_b128 v[178:181], v164 offset:1632
	s_waitcnt lgkmcnt(0)
	v_mfma_f32_32x32x16_bf16 v[112:127], v[166:169], v[198:201], v[112:127]
	v_mfma_f32_32x32x16_bf16 v[112:127], v[170:173], v[222:225], v[112:127]
	v_mfma_f32_32x32x16_bf16 v[112:127], v[174:177], v[226:229], v[112:127]
	v_mfma_f32_32x32x16_bf16 v[112:127], v[178:181], v[230:233], v[112:127]
	ds_read_b128 v[198:201], v241 offset:128
	ds_read_b128 v[222:225], v241 offset:160
	ds_read_b128 v[226:229], v241 offset:192
	ds_read_b128 v[230:233], v241 offset:224
	ds_read_b128 v[182:185], v164 offset:1664
	ds_read_b128 v[186:189], v164 offset:1696
	ds_read_b128 v[190:193], v164 offset:1728
	ds_read_b128 v[194:197], v164 offset:1760
	s_waitcnt lgkmcnt(0)
	v_mfma_f32_32x32x16_bf16 v[112:127], v[182:185], v[198:201], v[112:127]
	v_mfma_f32_32x32x16_bf16 v[112:127], v[186:189], v[222:225], v[112:127]
	v_mfma_f32_32x32x16_bf16 v[112:127], v[190:193], v[226:229], v[112:127]
	v_mfma_f32_32x32x16_bf16 v[112:127], v[194:197], v[230:233], v[112:127]
	s_nop 7
	s_nop 7
	v_cvt_pk_bf16_f32 v112, v112, v113
	v_cvt_pk_bf16_f32 v113, v114, v115
	global_store_dwordx2 v217, v[112:113], s[22:23] offset:0
	v_cvt_pk_bf16_f32 v116, v116, v117
	v_cvt_pk_bf16_f32 v117, v118, v119
	global_store_dwordx2 v217, v[116:117], s[22:23] offset:16
	v_cvt_pk_bf16_f32 v120, v120, v121
	v_cvt_pk_bf16_f32 v121, v122, v123
	global_store_dwordx2 v217, v[120:121], s[22:23] offset:32
	v_cvt_pk_bf16_f32 v124, v124, v125
	v_cvt_pk_bf16_f32 v125, v126, v127
	global_store_dwordx2 v217, v[124:125], s[22:23] offset:48
	s_branch .Lsc0_p3efa
.Lsc0_p3sfa:
	ds_read_b128 v[166:169], v244 offset:53248
	ds_read_b128 v[170:173], v244 offset:53280
	ds_read_b128 v[174:177], v244 offset:53312
	ds_read_b128 v[178:181], v244 offset:53344
	ds_read_b128 v[182:185], v207 offset:34816
	ds_read_b128 v[186:189], v207 offset:34848
	ds_read_b128 v[190:193], v207 offset:34880
	ds_read_b128 v[194:197], v207 offset:34912
	ds_read_b128 v[198:201], v207 offset:39424
	ds_read_b128 v[222:225], v207 offset:39456
	ds_read_b128 v[226:229], v207 offset:39488
	ds_read_b128 v[230:233], v207 offset:39520
	s_waitcnt lgkmcnt(4)
	v_mfma_f32_32x32x16_bf16 v[112:127], v[182:185], v[166:169], v[112:127]
	v_mfma_f32_32x32x16_bf16 v[112:127], v[186:189], v[170:173], v[112:127]
	v_mfma_f32_32x32x16_bf16 v[112:127], v[190:193], v[174:177], v[112:127]
	v_mfma_f32_32x32x16_bf16 v[112:127], v[194:197], v[178:181], v[112:127]
	s_waitcnt lgkmcnt(0)
	v_mfma_f32_32x32x16_bf16 v[128:143], v[198:201], v[166:169], v[128:143]
	v_mfma_f32_32x32x16_bf16 v[128:143], v[222:225], v[170:173], v[128:143]
	v_mfma_f32_32x32x16_bf16 v[128:143], v[226:229], v[174:177], v[128:143]
	v_mfma_f32_32x32x16_bf16 v[128:143], v[230:233], v[178:181], v[128:143]
	ds_read_b128 v[166:169], v208 offset:10240
	ds_read_b128 v[170:173], v208 offset:10272
	ds_read_b128 v[174:177], v208 offset:10304
	ds_read_b128 v[178:181], v208 offset:10336
	ds_read_b128 v[182:185], v208 offset:10368
	ds_read_b128 v[186:189], v208 offset:10400
	ds_read_b128 v[190:193], v208 offset:10432
	ds_read_b128 v[194:197], v208 offset:10464
	s_nop 7
	s_nop 7
	s_waitcnt lgkmcnt(0)
	v_mul_f32_e32 v112, v112, v166
	v_mul_f32_e32 v113, v113, v167
	v_mul_f32_e32 v114, v114, v168
	v_mul_f32_e32 v115, v115, v169
	v_mul_f32_e32 v116, v116, v170
	v_mul_f32_e32 v117, v117, v171
	v_mul_f32_e32 v118, v118, v172
	v_mul_f32_e32 v119, v119, v173
	v_mul_f32_e32 v120, v120, v174
	v_mul_f32_e32 v121, v121, v175
	v_mul_f32_e32 v122, v122, v176
	v_mul_f32_e32 v123, v123, v177
	v_mul_f32_e32 v124, v124, v178
	v_mul_f32_e32 v125, v125, v179
	v_mul_f32_e32 v126, v126, v180
	v_mul_f32_e32 v127, v127, v181
	v_mul_f32_e32 v128, v128, v182
	v_mul_f32_e32 v129, v129, v183
	v_mul_f32_e32 v130, v130, v184
	v_mul_f32_e32 v131, v131, v185
	v_mul_f32_e32 v132, v132, v186
	v_mul_f32_e32 v133, v133, v187
	v_mul_f32_e32 v134, v134, v188
	v_mul_f32_e32 v135, v135, v189
	v_mul_f32_e32 v136, v136, v190
	v_mul_f32_e32 v137, v137, v191
	v_mul_f32_e32 v138, v138, v192
	v_mul_f32_e32 v139, v139, v193
	v_mul_f32_e32 v140, v140, v194
	v_mul_f32_e32 v141, v141, v195
	v_mul_f32_e32 v142, v142, v196
	v_mul_f32_e32 v143, v143, v197
.Lsc0_p3efa:
	s_mov_b32 s0, 0x50000
	s_add_u32 s22, s22, s0
	s_addc_u32 s23, s23, 0
	s_waitcnt lgkmcnt(0)
	s_barrier
	s_cmp_lt_u32 s9, 2
	s_cbranch_scc0 .Lsc0_w1sfb
	s_waitcnt vmcnt(18)
	s_branch .Lsc0_w1efb

; DEV void scan_item_mfma(const Params& p, int g, int item, char* smem) {
;     ...
;     {
;       char* d = Qs + qrow * 272 + qc * 16;
;       *(uint4*)(d) = q0; *(uint4*)(d + 16 * 272) = q1; *(uint4*)(d + 32 * 272) = q2; *(uint4*)(d + 48 * 272) = q3;
;       d = Ks + qrow * 272 + qc * 16;
;       *(uint4*)(d) = k0; *(uint4*)(d + 16 * 272) = k1; *(uint4*)(d + 32 * 272) = k2; *(uint4*)(d + 48 * 272) = k3;
;       d = KTs + trow * 144 + tc * 16;
;       *(uint4*)(d) = t0; *(uint4*)(d + 32 * 144) = t1; *(uint4*)(d + 64 * 144) = t2; *(uint4*)(d + 96 * 144) = t3;
;       st8t(Vts + (vc * 8) * 144 + vrow * 2, vv);
;       if (tid < 128) decs[tid] = dd;
;       if (wave < 2 && ci > 0) {
;         u16* og = PHG + (otok + 32 * wave + 4 * hh) * 2560 + ocol + r;
; #pragma unroll
;         for (int i = 0; i < 8; ++i) {
;           og[(size_t)(((2 * i) & 3) + 8 * ((2 * i) >> 2)) * 2560] = (u16)(opk[i] & 0xffffu);
;           og[(size_t)(((2 * i + 1) & 3) + 8 * ((2 * i + 1) >> 2)) * 2560] = (u16)(opk[i] >> 16);
;         }
;       }
;       if (wave >= 2 && ci > 0) {
; #pragma unroll
;         for (int t = 0; t < 2; ++t) {
;           const int kt = 2 * (wave - 2) + t;
; #pragma unroll
;           for (int rg = 0; rg < 4; ++rg) {
;             const int kk0 = 32 * kt + 8 * rg + 4 * hh;
;             *(uint2*)(Sts + r * 272 + kk0 * 2) = make_uint2(pack2(accS[t][4 * rg + 0], accS[t][4 * rg + 1]),
;                                                             pack2(accS[t][4 * rg + 2], accS[t][4 * rg + 3]));
;           }
;         }
;       }
;     }
;     SCAN_BAR();
;     {
;       const int nn = (ci + 1 < NC) ? (dir ? NC - 2 - ci : ci + 1) : n;
;       SCAN_ISSUE(nn);
;     }
;     __builtin_amdgcn_sched_barrier(0);
;     {
;       const int jt = wave >> 1, st = wave & 1;
;       const bool active = dir ? (st >= jt) : (st <= jt);
;       f32x16 pa;
; #pragma unroll
;       for (int i = 0; i < 16; ++i) pa[i] = 0.f;
;       if (active) {
;         bf16x8 qa[8], kb[8];
; #pragma unroll
;         for (int ks = 0; ks < 8; ++ks) {
;           qa[ks] = *(const bf16x8*)(Qs + (32 * jt + r) * 272 + ks * 32 + hh * 16);
;           kb[ks] = *(const bf16x8*)(Ks + (32 * st + r) * 272 + ks * 32 + hh * 16);
;         }
;         __builtin_amdgcn_sched_barrier(0);
;         f32x16 p1;
; #pragma unroll
;         for (int i = 0; i < 16; ++i) p1[i] = 0.f;
; #pragma unroll
.Lsc0_w1efb:
	ds_write_b128 v234, v[56:59] offset:0
	ds_write_b128 v234, v[60:63] offset:4352
	ds_write_b128 v234, v[64:67] offset:8704
	ds_write_b128 v234, v[68:71] offset:13056
	ds_write_b128 v234, v[72:75] offset:17408
	ds_write_b128 v234, v[76:79] offset:21760
	ds_write_b128 v234, v[80:83] offset:26112
	ds_write_b128 v234, v[84:87] offset:30464
	ds_write_b128 v235, v[88:91] offset:34816
	ds_write_b128 v235, v[92:95] offset:39424
	ds_write_b128 v235, v[96:99] offset:44032
	ds_write_b128 v235, v[100:103] offset:48640
	ds_write_b16 v236, v104 offset:53248
	ds_write_b16_d16_hi v236, v104 offset:53392
	ds_write_b16 v236, v105 offset:53536
	ds_write_b16_d16_hi v236, v105 offset:53680
	ds_write_b16 v236, v106 offset:53824
	ds_write_b16_d16_hi v236, v106 offset:53968
	ds_write_b16 v236, v107 offset:54112
	ds_write_b16_d16_hi v236, v107 offset:54256
	ds_write_b32 v237, v108 offset:10240
	s_cmp_lt_u32 s9, 2
	s_cbranch_scc1 .Lsc0_p1ofb
	v_cvt_pk_bf16_f32 v166, v112, v113
	v_cvt_pk_bf16_f32 v167, v114, v115
	ds_write_b64 v238, v[166:167] offset:1536
	v_cvt_pk_bf16_f32 v168, v116, v117
	v_cvt_pk_bf16_f32 v169, v118, v119
	ds_write_b64 v238, v[168:169] offset:1552
	v_cvt_pk_bf16_f32 v170, v120, v121
	v_cvt_pk_bf16_f32 v171, v122, v123
	ds_write_b64 v238, v[170:171] offset:1568
	v_cvt_pk_bf16_f32 v172, v124, v125
	v_cvt_pk_bf16_f32 v173, v126, v127
	ds_write_b64 v238, v[172:173] offset:1584
	v_cvt_pk_bf16_f32 v174, v128, v129
	v_cvt_pk_bf16_f32 v175, v130, v131
	ds_write_b64 v238, v[174:175] offset:1600
	v_cvt_pk_bf16_f32 v176, v132, v133
	v_cvt_pk_bf16_f32 v177, v134, v135
	ds_write_b64 v238, v[176:177] offset:1616
	v_cvt_pk_bf16_f32 v178, v136, v137
	v_cvt_pk_bf16_f32 v179, v138, v139
	ds_write_b64 v238, v[178:179] offset:1632
	v_cvt_pk_bf16_f32 v180, v140, v141
	v_cvt_pk_bf16_f32 v181, v142, v143
	ds_write_b64 v238, v[180:181] offset:1648
.Lsc0_p1ofb:
	s_waitcnt lgkmcnt(0)
	s_barrier
	s_cmp_gt_i32 s10, 0
	s_cselect_b32 s1, 1, 0
	s_sub_i32 s10, s10, s1
	s_mul_i32 s0, s1, 0x10000
	s_add_u32 s12, s12, s0
	s_addc_u32 s13, s13, 0
	s_mul_i32 s0, s1, 0x10000
	s_add_u32 s14, s14, s0
	s_addc_u32 s15, s15, 0
	s_mul_i32 s0, s1, 0x20000
	s_add_u32 s16, s16, s0
	s_addc_u32 s17, s17, 0
	s_mul_i32 s0, s1, 0x50000
	s_add_u32 s18, s18, s0
	s_addc_u32 s19, s19, 0
	s_mul_i32 s0, s1, 0x800
	s_add_u32 s20, s20, s0
	s_addc_u32 s21, s21, 0
	global_load_dwordx4 v[56:59], v209, s[12:13]
	global_load_dwordx4 v[60:63], v210, s[12:13]
	global_load_dwordx4 v[64:67], v211, s[12:13]
	global_load_dwordx4 v[68:71], v212, s[12:13]
	global_load_dwordx4 v[72:75], v209, s[14:15]
	global_load_dwordx4 v[76:79], v210, s[14:15]
	global_load_dwordx4 v[80:83], v211, s[14:15]
	global_load_dwordx4 v[84:87], v212, s[14:15]
	global_load_dwordx4 v[88:91], v213, s[16:17] offset:-4096
	global_load_dwordx4 v[92:95], v213, s[16:17]
	global_load_dwordx4 v[96:99], v214, s[16:17] offset:-4096
	global_load_dwordx4 v[100:103], v214, s[16:17]
	global_load_dwordx4 v[104:107], v215, s[18:19]
	global_load_dword v108, v216, s[20:21]
	s_cmp_eq_u32 s9, 1
	s_cbranch_scc1 .Lsc0_p2efb
	ds_read_b128 v[166:169], v240
	ds_read_b128 v[170:173], v240 offset:32
	ds_read_b128 v[174:177], v240 offset:64
	ds_read_b128 v[178:181], v240 offset:96
	ds_read_b128 v[182:185], v242 offset:17408
	ds_read_b128 v[186:189], v242 offset:17440
	ds_read_b128 v[190:193], v242 offset:17472
	ds_read_b128 v[194:197], v242 offset:17504
	s_waitcnt lgkmcnt(0)
	v_mfma_f32_32x32x16_bf16 v[144:159], v[182:185], v[166:169], 0
	v_mfma_f32_32x32x16_bf16 v[144:159], v[186:189], v[170:173], v[144:159]
	v_mfma_f32_32x32x16_bf16 v[144:159], v[190:193], v[174:177], v[144:159]
	v_mfma_f32_32x32x16_bf16 v[144:159], v[194:197], v[178:181], v[144:159]
	ds_read_b128 v[166:169], v240 offset:128
	ds_read_b128 v[170:173], v240 offset:160
	ds_read_b128 v[174:177], v240 offset:192
	ds_read_b128 v[178:181], v240 offset:224
	ds_read_b128 v[182:185], v242 offset:17536
	ds_read_b128 v[186:189], v242 offset:17568
	ds_read_b128 v[190:193], v242 offset:17600
	ds_read_b128 v[194:197], v242 offset:17632
	s_waitcnt lgkmcnt(0)
	v_mfma_f32_32x32x16_bf16 v[144:159], v[182:185], v[166:169], v[144:159]
	v_mfma_f32_32x32x16_bf16 v[144:159], v[186:189], v[170:173], v[144:159]
	v_mfma_f32_32x32x16_bf16 v[144:159], v[190:193], v[174:177], v[144:159]
	v_mfma_f32_32x32x16_bf16 v[144:159], v[194:197], v[178:181], v[144:159]
	s_nop 7
	s_nop 7
	s_cmp_eq_u32 s9, 0
	s_cbranch_scc1 .Lsc0_p2mfb
	s_cmp_eq_u32 s9, 3
	s_cbranch_scc0 .Lsc0_p2nfb

; #define SCAN_BAR()                                        \
;   {                                                       \
;     asm volatile("s_waitcnt lgkmcnt(0)" ::: "memory");     \
;     __builtin_amdgcn_s_barrier();                         \
;     asm volatile("" ::: "memory");                         \
;   }
; DEV void scan_item_mfma(const Params& p, int g, int item, char* smem) {
;     ...
;   for (int ci = 0; ci < NC; ++ci) {
;     const int n = dir ? NC - 1 - ci : ci;
;     const size_t tok0 = ((size_t)b * NC + n) * 64;
;     {
;       char* d = Qs + qrow * 272 + qc * 16;
;       *(uint4*)(d) = q0; *(uint4*)(d + 16 * 272) = q1; *(uint4*)(d + 32 * 272) = q2; *(uint4*)(d + 48 * 272) = q3;
;       d = Ks + qrow * 272 + qc * 16;
;       *(uint4*)(d) = k0; *(uint4*)(d + 16 * 272) = k1; *(uint4*)(d + 32 * 272) = k2; *(uint4*)(d + 48 * 272) = k3;
;       d = KTs + trow * 144 + tc * 16;
;       *(uint4*)(d) = t0; *(uint4*)(d + 32 * 144) = t1; *(uint4*)(d + 64 * 144) = t2; *(uint4*)(d + 96 * 144) = t3;
;       st8t(Vts + (vc * 8) * 144 + vrow * 2, vv);
;       if (tid < 128) decs[tid] = dd;
;       if (wave < 2 && ci > 0) {
;         u16* og = PHG + (otok + 32 * wave + 4 * hh) * 2560 + ocol + r;
; #pragma unroll
;         for (int i = 0; i < 8; ++i) {
;           og[(size_t)(((2 * i) & 3) + 8 * ((2 * i) >> 2)) * 2560] = (u16)(opk[i] & 0xffffu);
;           og[(size_t)(((2 * i + 1) & 3) + 8 * ((2 * i + 1) >> 2)) * 2560] = (u16)(opk[i] >> 16);
;         }
;       }
;       if (wave >= 2 && ci > 0) {
; #pragma unroll
;         for (int t = 0; t < 2; ++t) {
;           const int kt = 2 * (wave - 2) + t;
; #pragma unroll
;           for (int rg = 0; rg < 4; ++rg) {
;             const int kk0 = 32 * kt + 8 * rg + 4 * hh;
;             *(uint2*)(Sts + r * 272 + kk0 * 2) = make_uint2(pack2(accS[t][4 * rg + 0], accS[t][4 * rg + 1]),
;                                                             pack2(accS[t][4 * rg + 2], accS[t][4 * rg + 3]));
;           }
;         }
;       }
;     }
;     SCAN_BAR();
;     {
;       const int nn = (ci + 1 < NC) ? (dir ? NC - 2 - ci : ci + 1) : n;
;       SCAN_ISSUE(nn);
.Lsc0_p3efb:
	s_mov_b32 s0, 0x50000
	s_add_u32 s22, s22, s0
	s_addc_u32 s23, s23, 0
	s_waitcnt lgkmcnt(0)
	s_barrier
	s_lshr_b32 s8, s7, 1
	s_sub_i32 s8, s8, 2
.Lsc0_loop:
	s_cmp_lt_u32 s9, 2
	s_cbranch_scc0 .Lsc0_w1sa
	s_waitcnt vmcnt(22)
	s_branch .Lsc0_w1ea

; #define SCAN_BAR()                                        \
;   {                                                       \
;     asm volatile("s_waitcnt lgkmcnt(0)" ::: "memory");     \
;     __builtin_amdgcn_s_barrier();                         \
;     asm volatile("" ::: "memory");                         \
;   }
; DEV void scan_item_mfma(const Params& p, int g, int item, char* smem) {
;     ...
;       otok = tok0;
;     } else {
;       const int kt0 = 2 * (wave - 2);
;       bf16x8 ka[2][4], vb[4];
; #pragma unroll
;       for (int ks = 0; ks < 4; ++ks) {
;         vb[ks] = *(const bf16x8*)(Vts + r * 144 + ks * 32 + hh * 16);
;         ka[0][ks] = *(const bf16x8*)(KTs + (32 * kt0 + r) * 144 + ks * 32 + hh * 16);
;         ka[1][ks] = *(const bf16x8*)(KTs + (32 * (kt0 + 1) + r) * 144 + ks * 32 + hh * 16);
;       }
;       __builtin_amdgcn_sched_barrier(0);
; #pragma unroll
;       for (int ks = 0; ks < 4; ++ks) {
;         accS[0] = __builtin_amdgcn_mfma_f32_32x32x16_bf16(ka[0][ks], vb[ks], accS[0], 0, 0, 0);
;         accS[1] = __builtin_amdgcn_mfma_f32_32x32x16_bf16(ka[1][ks], vb[ks], accS[1], 0, 0, 0);
;       }
; #pragma unroll
;       for (int t = 0; t < 2; ++t)
; #pragma unroll
;         for (int i = 0; i < 16; ++i) accS[t][i] *= decs[32 * (kt0 + t) + (i & 3) + 8 * (i >> 2) + 4 * hh];
;     }
;     SCAN_BAR();
;   }
.Lsc0_p3ea:
	s_mov_b32 s0, 0x50000
	s_add_u32 s22, s22, s0
	s_addc_u32 s23, s23, 0
	s_waitcnt lgkmcnt(0)
	s_barrier
	s_cmp_lt_u32 s9, 2
	s_cbranch_scc0 .Lsc0_w1sb
	s_waitcnt vmcnt(22)
	s_branch .Lsc0_w1eb

; #define SCAN_BAR()                                        \
;   {                                                       \
;     asm volatile("s_waitcnt lgkmcnt(0)" ::: "memory");     \
;     __builtin_amdgcn_s_barrier();                         \
;     asm volatile("" ::: "memory");                         \
;   }
; DEV void scan_item_mfma(const Params& p, int g, int item, char* smem) {
;     ...
;   for (int ci = 0; ci < NC; ++ci) {
;     const int n = dir ? NC - 1 - ci : ci;
;     const size_t tok0 = ((size_t)b * NC + n) * 64;
;     {
;       char* d = Qs + qrow * 272 + qc * 16;
;       *(uint4*)(d) = q0; *(uint4*)(d + 16 * 272) = q1; *(uint4*)(d + 32 * 272) = q2; *(uint4*)(d + 48 * 272) = q3;
;       d = Ks + qrow * 272 + qc * 16;
;       *(uint4*)(d) = k0; *(uint4*)(d + 16 * 272) = k1; *(uint4*)(d + 32 * 272) = k2; *(uint4*)(d + 48 * 272) = k3;
;       d = KTs + trow * 144 + tc * 16;
;       *(uint4*)(d) = t0; *(uint4*)(d + 32 * 144) = t1; *(uint4*)(d + 64 * 144) = t2; *(uint4*)(d + 96 * 144) = t3;
;       st8t(Vts + (vc * 8) * 144 + vrow * 2, vv);
;       if (tid < 128) decs[tid] = dd;
;     ...
;     SCAN_BAR();
;   }
.Lsc0_p3eb:
	s_mov_b32 s0, 0x50000
	s_add_u32 s22, s22, s0
	s_addc_u32 s23, s23, 0
	s_waitcnt lgkmcnt(0)
	s_barrier
	s_sub_i32 s8, s8, 1
	s_cmp_lg_u32 s8, 0
	s_cbranch_scc1 .Lsc0_loop
	s_cmp_lt_u32 s9, 2
	s_cbranch_scc0 .Lsc0_w1sta
	s_waitcnt vmcnt(22)
	s_branch .Lsc0_w1eta

; DEV u16 f2bf(float f) { return (u16)(pack2(f, f) & 0xffffu); }
; #define SCAN_BAR()                                        \
;   {                                                       \
;     asm volatile("s_waitcnt lgkmcnt(0)" ::: "memory");     \
;     __builtin_amdgcn_s_barrier();                         \
;     asm volatile("" ::: "memory");                         \
;   }
; DEV void scan_item_mfma(const Params& p, int g, int item, char* smem) {
;     ...
;     SCAN_BAR();
;     {
;       const int nn = (ci + 1 < NC) ? (dir ? NC - 2 - ci : ci + 1) : n;
;       SCAN_ISSUE(nn);
;     }
;     __builtin_amdgcn_sched_barrier(0);
;     {
;       const int jt = wave >> 1, st = wave & 1;
;       const bool active = dir ? (st >= jt) : (st <= jt);
;       f32x16 pa;
; #pragma unroll
;       for (int i = 0; i < 16; ++i) pa[i] = 0.f;
;       if (active) {
;         bf16x8 qa[8], kb[8];
; #pragma unroll
;         for (int ks = 0; ks < 8; ++ks) {
;           qa[ks] = *(const bf16x8*)(Qs + (32 * jt + r) * 272 + ks * 32 + hh * 16);
;           kb[ks] = *(const bf16x8*)(Ks + (32 * st + r) * 272 + ks * 32 + hh * 16);
;         }
;         __builtin_amdgcn_sched_barrier(0);
;         f32x16 p1;
; #pragma unroll
;         for (int i = 0; i < 16; ++i) p1[i] = 0.f;
; #pragma unroll
;         for (int ks = 0; ks < 4; ++ks) {
;           pa = __builtin_amdgcn_mfma_f32_32x32x16_bf16(qa[2 * ks], kb[2 * ks], pa, 0, 0, 0);
;           p1 = __builtin_amdgcn_mfma_f32_32x32x16_bf16(qa[2 * ks + 1], kb[2 * ks + 1], p1, 0, 0, 0);
;         }
; #pragma unroll
;         for (int i = 0; i < 16; ++i) pa[i] += p1[i];
;       }
; #pragma unroll
;       for (int i = 0; i < 16; ++i) {
;         const int j = 32 * jt + (i & 3) + 8 * (i >> 2) + 4 * hh;
;         const int s_ = 32 * st + r;
;         const bool keep = dir ? (s_ >= j) : (s_ <= j);
;         *(u16*)(Ps + j * 144 + s_ * 2) = keep ? f2bf(pa[i]) : (u16)0;
;       }
;     }
.Lsc0_p1ota:
	s_waitcnt lgkmcnt(0)
	s_barrier
	s_cmp_eq_u32 s9, 1
	s_cbranch_scc1 .Lsc0_p2eta
	ds_read_b128 v[166:169], v240
	ds_read_b128 v[170:173], v240 offset:32
	ds_read_b128 v[174:177], v240 offset:64
	ds_read_b128 v[178:181], v240 offset:96
	ds_read_b128 v[182:185], v242 offset:17408
	ds_read_b128 v[186:189], v242 offset:17440
	ds_read_b128 v[190:193], v242 offset:17472
	ds_read_b128 v[194:197], v242 offset:17504
	s_waitcnt lgkmcnt(0)
	v_mfma_f32_32x32x16_bf16 v[144:159], v[182:185], v[166:169], 0
	v_mfma_f32_32x32x16_bf16 v[144:159], v[186:189], v[170:173], v[144:159]
	v_mfma_f32_32x32x16_bf16 v[144:159], v[190:193], v[174:177], v[144:159]
	v_mfma_f32_32x32x16_bf16 v[144:159], v[194:197], v[178:181], v[144:159]
	ds_read_b128 v[166:169], v240 offset:128
	ds_read_b128 v[170:173], v240 offset:160
	ds_read_b128 v[174:177], v240 offset:192
	ds_read_b128 v[178:181], v240 offset:224
	ds_read_b128 v[182:185], v242 offset:17536
	ds_read_b128 v[186:189], v242 offset:17568
	ds_read_b128 v[190:193], v242 offset:17600
	ds_read_b128 v[194:197], v242 offset:17632
	s_waitcnt lgkmcnt(0)
	v_mfma_f32_32x32x16_bf16 v[144:159], v[182:185], v[166:169], v[144:159]
	v_mfma_f32_32x32x16_bf16 v[144:159], v[186:189], v[170:173], v[144:159]
	v_mfma_f32_32x32x16_bf16 v[144:159], v[190:193], v[174:177], v[144:159]
	v_mfma_f32_32x32x16_bf16 v[144:159], v[194:197], v[178:181], v[144:159]
	s_nop 7
	s_nop 7
	s_cmp_eq_u32 s9, 0
	s_cbranch_scc1 .Lsc0_p2mta
	s_cmp_eq_u32 s9, 3
	s_cbranch_scc0 .Lsc0_p2nta

; #define SCAN_BAR()                                        \
;   {                                                       \
;     asm volatile("s_waitcnt lgkmcnt(0)" ::: "memory");     \
;     __builtin_amdgcn_s_barrier();                         \
;     asm volatile("" ::: "memory");                         \
;   }
; DEV void scan_item_mfma(const Params& p, int g, int item, char* smem) {
;     ...
;     SCAN_BAR();
;   }
;   if (wave < 2) {
;     u16* og = PHG + (otok + 32 * wave + 4 * hh) * 2560 + ocol + r;
.Lsc0_p3eta:
	s_mov_b32 s0, 0x50000
	s_add_u32 s22, s22, s0
	s_addc_u32 s23, s23, 0
	s_waitcnt lgkmcnt(0)
	s_barrier
	s_cmp_lt_u32 s9, 2
	s_cbranch_scc0 .Lsc0_w1stb
	s_waitcnt vmcnt(0)
	s_branch .Lsc0_w1etb

; DEV void scan_item_mfma(const Params& p, int g, int item, char* smem) {
;     ...
;   for (int e = tid; e < 8704 / 16; e += 256) ((uint4*)Sts)[e] = make_uint4(0, 0, 0, 0);
;   f32x16 accS[2];
; #pragma unroll
;   for (int t = 0; t < 2; ++t)
; #pragma unroll
;     for (int i = 0; i < 16; ++i) accS[t][i] = 0.f;
;   const int ocol = (dir ? 1024 : 0) + h * 128 + vs * 32;
;   uint4 q0, q1, q2, q3, k0, k1, k2, k3, t0, t1, t2, t3, vv;
;   float dd = 0.f;
;   const int qrow = tid >> 4, qc = tid & 15;
;   const int trow = tid >> 3, tc = tid & 7;
;   const int vrow = tid >> 2, vc = tid & 3;
;     ...
;   unsigned opk[8] = {0u, 0u, 0u, 0u, 0u, 0u, 0u, 0u};
;   size_t otok = 0;
;   SCAN_ISSUE(dir ? NC - 1 : 0);
.Lsc0_p3etb:
	s_mov_b32 s0, 0x50000
	s_add_u32 s22, s22, s0
	s_addc_u32 s23, s23, 0
	s_waitcnt lgkmcnt(0)
	s_barrier
	s_branch .Lscan_done
.Lscan_d1:
	s_mul_i32 s11, s6, s7
	s_add_i32 s11, s11, s7
	s_sub_i32 s11, s11, 1
	s_add_u32 s12, s64, 0x4000000
	s_addc_u32 s13, s65, 0
	s_mul_i32 s0, s11, 0x10000
	s_add_u32 s12, s12, s0
	s_addc_u32 s13, s13, 0
	s_mul_i32 s0, s5, 0x100
	s_add_u32 s12, s12, s0
	s_addc_u32 s13, s13, 0
	s_add_u32 s14, s12, 0x2000000
	s_addc_u32 s15, s13, 0
	s_add_u32 s16, s88, 0x3d5c100
	s_addc_u32 s17, s89, 0
	s_mul_i32 s0, s11, 0x20000
	s_add_u32 s16, s16, s0
	s_addc_u32 s17, s17, 0
	s_mul_i32 s0, s5, 0x4000
	s_add_u32 s16, s16, s0
	s_addc_u32 s17, s17, 0
	s_add_u32 s18, s88, 0xdd4c500
	s_addc_u32 s19, s89, 0
	s_mul_i32 s0, s11, 0x50000
	s_add_u32 s18, s18, s0
	s_addc_u32 s19, s19, 0
	s_mul_i32 s0, s5, 0x100
	s_add_u32 s18, s18, s0
	s_addc_u32 s19, s19, 0
	s_mul_i32 s0, s3, 0x40
	s_add_u32 s18, s18, s0
	s_addc_u32 s19, s19, 0
	s_add_u32 s20, s88, 0x3c4c100
	s_addc_u32 s21, s89, 0
	s_mul_i32 s0, s11, 0x800
	s_add_u32 s20, s20, s0
	s_addc_u32 s21, s21, 0
	s_mul_i32 s0, s5, 0x200
	s_add_u32 s20, s20, s0
	s_addc_u32 s21, s21, 0
	s_add_u32 s22, s88, 0xdd4c900
	s_addc_u32 s23, s89, 0
	s_mul_i32 s0, s11, 0x50000
	s_add_u32 s22, s22, s0
	s_addc_u32 s23, s23, 0
	s_mul_i32 s0, s5, 0x100
	s_add_u32 s22, s22, s0
	s_addc_u32 s23, s23, 0
	s_mul_i32 s0, s3, 0x40
	s_add_u32 s22, s22, s0
	s_addc_u32 s23, s23, 0
	v_cmp_ge_i32_e64 s[34:35], 0, v218
	v_cmp_ge_i32_e64 s[36:37], 1, v218
	v_cmp_ge_i32_e64 s[38:39], 2, v218
	v_cmp_ge_i32_e64 s[40:41], 3, v218
	v_cmp_ge_i32_e64 s[42:43], 8, v218
	v_cmp_ge_i32_e64 s[44:45], 9, v218
	v_cmp_ge_i32_e64 s[46:47], 10, v218
	v_cmp_ge_i32_e64 s[48:49], 11, v218
	v_cmp_ge_i32_e64 s[50:51], 16, v218
	v_cmp_ge_i32_e64 s[52:53], 17, v218
	v_cmp_ge_i32_e64 s[54:55], 18, v218
	v_cmp_ge_i32_e64 s[56:57], 19, v218
	v_cmp_ge_i32_e64 s[58:59], 24, v218
	v_cmp_ge_i32_e64 s[60:61], 25, v218
	v_cmp_ge_i32_e64 s[62:63], 26, v218
	v_cmp_ge_i32_e64 s[64:65], 27, v218
	v_mov_b32_e32 v144, 0
	v_mov_b32_e32 v145, 0
	v_mov_b32_e32 v146, 0
	v_mov_b32_e32 v147, 0
	v_mov_b64_e32 v[112:113], v[144:145]
	v_mov_b64_e32 v[114:115], v[144:145]
	v_mov_b64_e32 v[116:117], v[144:145]
	v_mov_b64_e32 v[118:119], v[144:145]
	v_mov_b64_e32 v[120:121], v[144:145]
	v_mov_b64_e32 v[122:123], v[144:145]
	v_mov_b64_e32 v[124:125], v[144:145]
	v_mov_b64_e32 v[126:127], v[144:145]
	v_mov_b64_e32 v[128:129], v[144:145]
	v_mov_b64_e32 v[130:131], v[144:145]
	v_mov_b64_e32 v[132:133], v[144:145]
	v_mov_b64_e32 v[134:135], v[144:145]
	v_mov_b64_e32 v[136:137], v[144:145]
	v_mov_b64_e32 v[138:139], v[144:145]
	v_mov_b64_e32 v[140:141], v[144:145]
	v_mov_b64_e32 v[142:143], v[144:145]
	v_lshl_add_u32 v220, v53, 5, s92
	v_add_u32_e32 v220, 0x10000, v220
	ds_write_b128 v220, v[144:147] offset:1536
	ds_write_b128 v220, v[144:147] offset:1552
	v_and_b32_e32 v221, 31, v53
	v_lshl_add_u32 v221, v221, 4, s92
	v_add_u32_e32 v221, 0x10000, v221
	ds_write_b128 v221, v[144:147] offset:9728
	s_cmp_eq_u32 s9, 2
	s_cbranch_scc0 .Lsc1_nz
	v_mul_u32_u24_e32 v219, 24, v109
	v_add_u32_e32 v219, v239, v219
	ds_write_b128 v219, v[144:147] offset:57856
	ds_write_b128 v219, v[144:147] offset:57872
.Lsc1_nz:
	global_load_dwordx4 v[0:3], v209, s[12:13]
	global_load_dwordx4 v[4:7], v210, s[12:13]
	global_load_dwordx4 v[8:11], v211, s[12:13]
	global_load_dwordx4 v[12:15], v212, s[12:13]
	global_load_dwordx4 v[16:19], v209, s[14:15]
	global_load_dwordx4 v[20:23], v210, s[14:15]
	global_load_dwordx4 v[24:27], v211, s[14:15]
	global_load_dwordx4 v[28:31], v212, s[14:15]
	global_load_dwordx4 v[32:35], v213, s[16:17] offset:-4096
	global_load_dwordx4 v[36:39], v213, s[16:17]
	global_load_dwordx4 v[40:43], v214, s[16:17] offset:-4096
	global_load_dwordx4 v[44:47], v214, s[16:17]
	global_load_dwordx4 v[48:51], v215, s[18:19]
	global_load_dword v52, v216, s[20:21]
	s_sub_i32 s10, s7, 1
	s_cmp_gt_i32 s10, 0
	s_cselect_b32 s1, 1, 0
	s_sub_i32 s10, s10, s1
	s_mul_i32 s0, s1, 0x10000
	s_sub_u32 s12, s12, s0
	s_subb_u32 s13, s13, 0
	s_mul_i32 s0, s1, 0x10000
	s_sub_u32 s14, s14, s0
	s_subb_u32 s15, s15, 0
	s_mul_i32 s0, s1, 0x20000
	s_sub_u32 s16, s16, s0
	s_subb_u32 s17, s17, 0
	s_mul_i32 s0, s1, 0x50000
	s_sub_u32 s18, s18, s0
	s_subb_u32 s19, s19, 0
	s_mul_i32 s0, s1, 0x800
	s_sub_u32 s20, s20, s0
	s_subb_u32 s21, s21, 0
	global_load_dwordx4 v[56:59], v209, s[12:13]
	global_load_dwordx4 v[60:63], v210, s[12:13]
	global_load_dwordx4 v[64:67], v211, s[12:13]
	global_load_dwordx4 v[68:71], v212, s[12:13]
	global_load_dwordx4 v[72:75], v209, s[14:15]
	global_load_dwordx4 v[76:79], v210, s[14:15]
	global_load_dwordx4 v[80:83], v211, s[14:15]
	global_load_dwordx4 v[84:87], v212, s[14:15]
	global_load_dwordx4 v[88:91], v213, s[16:17] offset:-4096
	global_load_dwordx4 v[92:95], v213, s[16:17]
	global_load_dwordx4 v[96:99], v214, s[16:17] offset:-4096
	global_load_dwordx4 v[100:103], v214, s[16:17]
	global_load_dwordx4 v[104:107], v215, s[18:19]
	global_load_dword v108, v216, s[20:21]
	s_cmp_lt_u32 s9, 2
	s_cbranch_scc0 .Lsc1_w1sfa
	s_waitcnt vmcnt(14)
	s_branch .Lsc1_w1efa

; DEV u16 f2bf(float f) { return (u16)(pack2(f, f) & 0xffffu); }
; #define SCAN_BAR()                                        \
;   {                                                       \
;     asm volatile("s_waitcnt lgkmcnt(0)" ::: "memory");     \
;     __builtin_amdgcn_s_barrier();                         \
;     asm volatile("" ::: "memory");                         \
;   }
; DEV void scan_item_mfma(const Params& p, int g, int item, char* smem) {
;     ...
;     SCAN_BAR();
;     {
;       const int nn = (ci + 1 < NC) ? (dir ? NC - 2 - ci : ci + 1) : n;
;       SCAN_ISSUE(nn);
;     }
;     __builtin_amdgcn_sched_barrier(0);
;     {
;       const int jt = wave >> 1, st = wave & 1;
;       const bool active = dir ? (st >= jt) : (st <= jt);
;       f32x16 pa;
; #pragma unroll
;       for (int i = 0; i < 16; ++i) pa[i] = 0.f;
;       if (active) {
;         bf16x8 qa[8], kb[8];
; #pragma unroll
;         for (int ks = 0; ks < 8; ++ks) {
;           qa[ks] = *(const bf16x8*)(Qs + (32 * jt + r) * 272 + ks * 32 + hh * 16);
;           kb[ks] = *(const bf16x8*)(Ks + (32 * st + r) * 272 + ks * 32 + hh * 16);
;         }
;         __builtin_amdgcn_sched_barrier(0);
;         f32x16 p1;
; #pragma unroll
;         for (int i = 0; i < 16; ++i) p1[i] = 0.f;
; #pragma unroll
;         for (int ks = 0; ks < 4; ++ks) {
;           pa = __builtin_amdgcn_mfma_f32_32x32x16_bf16(qa[2 * ks], kb[2 * ks], pa, 0, 0, 0);
;           p1 = __builtin_amdgcn_mfma_f32_32x32x16_bf16(qa[2 * ks + 1], kb[2 * ks + 1], p1, 0, 0, 0);
;         }
; #pragma unroll
;         for (int i = 0; i < 16; ++i) pa[i] += p1[i];
;       }
; #pragma unroll
;       for (int i = 0; i < 16; ++i) {
;         const int j = 32 * jt + (i & 3) + 8 * (i >> 2) + 4 * hh;
;         const int s_ = 32 * st + r;
;         const bool keep = dir ? (s_ >= j) : (s_ <= j);
;         *(u16*)(Ps + j * 144 + s_ * 2) = keep ? f2bf(pa[i]) : (u16)0;
;       }
;     }
.Lsc1_p1ofa:
	s_waitcnt lgkmcnt(0)
	s_barrier
	s_cmp_gt_i32 s10, 0
	s_cselect_b32 s1, 1, 0
	s_sub_i32 s10, s10, s1
	s_mul_i32 s0, s1, 0x10000
	s_sub_u32 s12, s12, s0
	s_subb_u32 s13, s13, 0
	s_mul_i32 s0, s1, 0x10000
	s_sub_u32 s14, s14, s0
	s_subb_u32 s15, s15, 0
	s_mul_i32 s0, s1, 0x20000
	s_sub_u32 s16, s16, s0
	s_subb_u32 s17, s17, 0
	s_mul_i32 s0, s1, 0x50000
	s_sub_u32 s18, s18, s0
	s_subb_u32 s19, s19, 0
	s_mul_i32 s0, s1, 0x800
	s_sub_u32 s20, s20, s0
	s_subb_u32 s21, s21, 0
	global_load_dwordx4 v[0:3], v209, s[12:13]
	global_load_dwordx4 v[4:7], v210, s[12:13]
	global_load_dwordx4 v[8:11], v211, s[12:13]
	global_load_dwordx4 v[12:15], v212, s[12:13]
	global_load_dwordx4 v[16:19], v209, s[14:15]
	global_load_dwordx4 v[20:23], v210, s[14:15]
	global_load_dwordx4 v[24:27], v211, s[14:15]
	global_load_dwordx4 v[28:31], v212, s[14:15]
	global_load_dwordx4 v[32:35], v213, s[16:17] offset:-4096
	global_load_dwordx4 v[36:39], v213, s[16:17]
	global_load_dwordx4 v[40:43], v214, s[16:17] offset:-4096
	global_load_dwordx4 v[44:47], v214, s[16:17]
	global_load_dwordx4 v[48:51], v215, s[18:19]
	global_load_dword v52, v216, s[20:21]
	s_cmp_eq_u32 s9, 2
	s_cbranch_scc1 .Lsc1_p2efa
	ds_read_b128 v[166:169], v240
	ds_read_b128 v[170:173], v240 offset:32
	ds_read_b128 v[174:177], v240 offset:64
	ds_read_b128 v[178:181], v240 offset:96
	ds_read_b128 v[182:185], v242 offset:17408
	ds_read_b128 v[186:189], v242 offset:17440
	ds_read_b128 v[190:193], v242 offset:17472
	ds_read_b128 v[194:197], v242 offset:17504
	s_waitcnt lgkmcnt(0)
	v_mfma_f32_32x32x16_bf16 v[144:159], v[182:185], v[166:169], 0
	v_mfma_f32_32x32x16_bf16 v[144:159], v[186:189], v[170:173], v[144:159]
	v_mfma_f32_32x32x16_bf16 v[144:159], v[190:193], v[174:177], v[144:159]
	v_mfma_f32_32x32x16_bf16 v[144:159], v[194:197], v[178:181], v[144:159]
	ds_read_b128 v[166:169], v240 offset:128
	ds_read_b128 v[170:173], v240 offset:160
	ds_read_b128 v[174:177], v240 offset:192
	ds_read_b128 v[178:181], v240 offset:224
	ds_read_b128 v[182:185], v242 offset:17536
	ds_read_b128 v[186:189], v242 offset:17568
	ds_read_b128 v[190:193], v242 offset:17600
	ds_read_b128 v[194:197], v242 offset:17632
	s_waitcnt lgkmcnt(0)
	v_mfma_f32_32x32x16_bf16 v[144:159], v[182:185], v[166:169], v[144:159]
	v_mfma_f32_32x32x16_bf16 v[144:159], v[186:189], v[170:173], v[144:159]
	v_mfma_f32_32x32x16_bf16 v[144:159], v[190:193], v[174:177], v[144:159]
	v_mfma_f32_32x32x16_bf16 v[144:159], v[194:197], v[178:181], v[144:159]
	s_nop 7
	s_nop 7
	s_cmp_eq_u32 s9, 0
	s_cbranch_scc1 .Lsc1_p2mfa
	s_cmp_eq_u32 s9, 3
	s_cbranch_scc0 .Lsc1_p2nfa

; #define SCAN_BAR()                                        \
;   {                                                       \
;     asm volatile("s_waitcnt lgkmcnt(0)" ::: "memory");     \
;     __builtin_amdgcn_s_barrier();                         \
;     asm volatile("" ::: "memory");                         \
;   }
; DEV void scan_item_mfma(const Params& p, int g, int item, char* smem) {
;     ...
;     {
;       char* d = Qs + qrow * 272 + qc * 16;
;       *(uint4*)(d) = q0; *(uint4*)(d + 16 * 272) = q1; *(uint4*)(d + 32 * 272) = q2; *(uint4*)(d + 48 * 272) = q3;
;       d = Ks + qrow * 272 + qc * 16;
;       *(uint4*)(d) = k0; *(uint4*)(d + 16 * 272) = k1; *(uint4*)(d + 32 * 272) = k2; *(uint4*)(d + 48 * 272) = k3;
;       d = KTs + trow * 144 + tc * 16;
;       *(uint4*)(d) = t0; *(uint4*)(d + 32 * 144) = t1; *(uint4*)(d + 64 * 144) = t2; *(uint4*)(d + 96 * 144) = t3;
;       st8t(Vts + (vc * 8) * 144 + vrow * 2, vv);
;       if (tid < 128) decs[tid] = dd;
;     ...
;     SCAN_BAR();
;   }
.Lsc1_p3efa:
	s_mov_b32 s0, 0x50000
	s_sub_u32 s22, s22, s0
	s_subb_u32 s23, s23, 0
	s_waitcnt lgkmcnt(0)
	s_barrier
	s_cmp_lt_u32 s9, 2
	s_cbranch_scc0 .Lsc1_w1sfb
	s_waitcnt vmcnt(18)
	s_branch .Lsc1_w1efb

; DEV u16 f2bf(float f) { return (u16)(pack2(f, f) & 0xffffu); }
; #define SCAN_BAR()                                        \
;   {                                                       \
;     asm volatile("s_waitcnt lgkmcnt(0)" ::: "memory");     \
;     __builtin_amdgcn_s_barrier();                         \
;     asm volatile("" ::: "memory");                         \
;   }
; DEV void scan_item_mfma(const Params& p, int g, int item, char* smem) {
;     ...
;     SCAN_BAR();
;     {
;       const int nn = (ci + 1 < NC) ? (dir ? NC - 2 - ci : ci + 1) : n;
;       SCAN_ISSUE(nn);
;     }
;     __builtin_amdgcn_sched_barrier(0);
;     {
;       const int jt = wave >> 1, st = wave & 1;
;       const bool active = dir ? (st >= jt) : (st <= jt);
;       f32x16 pa;
; #pragma unroll
;       for (int i = 0; i < 16; ++i) pa[i] = 0.f;
;       if (active) {
;         bf16x8 qa[8], kb[8];
; #pragma unroll
;         for (int ks = 0; ks < 8; ++ks) {
;           qa[ks] = *(const bf16x8*)(Qs + (32 * jt + r) * 272 + ks * 32 + hh * 16);
;           kb[ks] = *(const bf16x8*)(Ks + (32 * st + r) * 272 + ks * 32 + hh * 16);
;         }
;         __builtin_amdgcn_sched_barrier(0);
;         f32x16 p1;
; #pragma unroll
;         for (int i = 0; i < 16; ++i) p1[i] = 0.f;
; #pragma unroll
;         for (int ks = 0; ks < 4; ++ks) {
;           pa = __builtin_amdgcn_mfma_f32_32x32x16_bf16(qa[2 * ks], kb[2 * ks], pa, 0, 0, 0);
;           p1 = __builtin_amdgcn_mfma_f32_32x32x16_bf16(qa[2 * ks + 1], kb[2 * ks + 1], p1, 0, 0, 0);
;         }
; #pragma unroll
;         for (int i = 0; i < 16; ++i) pa[i] += p1[i];
;       }
; #pragma unroll
;       for (int i = 0; i < 16; ++i) {
;         const int j = 32 * jt + (i & 3) + 8 * (i >> 2) + 4 * hh;
;         const int s_ = 32 * st + r;
;         const bool keep = dir ? (s_ >= j) : (s_ <= j);
;         *(u16*)(Ps + j * 144 + s_ * 2) = keep ? f2bf(pa[i]) : (u16)0;
;       }
;     }
.Lsc1_p1ofb:
	s_waitcnt lgkmcnt(0)
	s_barrier
	s_cmp_gt_i32 s10, 0
	s_cselect_b32 s1, 1, 0
	s_sub_i32 s10, s10, s1
	s_mul_i32 s0, s1, 0x10000
	s_sub_u32 s12, s12, s0
	s_subb_u32 s13, s13, 0
	s_mul_i32 s0, s1, 0x10000
	s_sub_u32 s14, s14, s0
	s_subb_u32 s15, s15, 0
	s_mul_i32 s0, s1, 0x20000
	s_sub_u32 s16, s16, s0
	s_subb_u32 s17, s17, 0
	s_mul_i32 s0, s1, 0x50000
	s_sub_u32 s18, s18, s0
	s_subb_u32 s19, s19, 0
	s_mul_i32 s0, s1, 0x800
	s_sub_u32 s20, s20, s0
	s_subb_u32 s21, s21, 0
	global_load_dwordx4 v[56:59], v209, s[12:13]
	global_load_dwordx4 v[60:63], v210, s[12:13]
	global_load_dwordx4 v[64:67], v211, s[12:13]
	global_load_dwordx4 v[68:71], v212, s[12:13]
	global_load_dwordx4 v[72:75], v209, s[14:15]
	global_load_dwordx4 v[76:79], v210, s[14:15]
	global_load_dwordx4 v[80:83], v211, s[14:15]
	global_load_dwordx4 v[84:87], v212, s[14:15]
	global_load_dwordx4 v[88:91], v213, s[16:17] offset:-4096
	global_load_dwordx4 v[92:95], v213, s[16:17]
	global_load_dwordx4 v[96:99], v214, s[16:17] offset:-4096
	global_load_dwordx4 v[100:103], v214, s[16:17]
	global_load_dwordx4 v[104:107], v215, s[18:19]
	global_load_dword v108, v216, s[20:21]
	s_cmp_eq_u32 s9, 2
	s_cbranch_scc1 .Lsc1_p2efb
	ds_read_b128 v[166:169], v240
	ds_read_b128 v[170:173], v240 offset:32
	ds_read_b128 v[174:177], v240 offset:64
	ds_read_b128 v[178:181], v240 offset:96
	ds_read_b128 v[182:185], v242 offset:17408
	ds_read_b128 v[186:189], v242 offset:17440
	ds_read_b128 v[190:193], v242 offset:17472
	ds_read_b128 v[194:197], v242 offset:17504
	s_waitcnt lgkmcnt(0)
	v_mfma_f32_32x32x16_bf16 v[144:159], v[182:185], v[166:169], 0
	v_mfma_f32_32x32x16_bf16 v[144:159], v[186:189], v[170:173], v[144:159]
	v_mfma_f32_32x32x16_bf16 v[144:159], v[190:193], v[174:177], v[144:159]
	v_mfma_f32_32x32x16_bf16 v[144:159], v[194:197], v[178:181], v[144:159]
	ds_read_b128 v[166:169], v240 offset:128
	ds_read_b128 v[170:173], v240 offset:160
	ds_read_b128 v[174:177], v240 offset:192
	ds_read_b128 v[178:181], v240 offset:224
	ds_read_b128 v[182:185], v242 offset:17536
	ds_read_b128 v[186:189], v242 offset:17568
	ds_read_b128 v[190:193], v242 offset:17600
	ds_read_b128 v[194:197], v242 offset:17632
	s_waitcnt lgkmcnt(0)
	v_mfma_f32_32x32x16_bf16 v[144:159], v[182:185], v[166:169], v[144:159]
	v_mfma_f32_32x32x16_bf16 v[144:159], v[186:189], v[170:173], v[144:159]
	v_mfma_f32_32x32x16_bf16 v[144:159], v[190:193], v[174:177], v[144:159]
	v_mfma_f32_32x32x16_bf16 v[144:159], v[194:197], v[178:181], v[144:159]
	s_nop 7
	s_nop 7
	s_cmp_eq_u32 s9, 0
	s_cbranch_scc1 .Lsc1_p2mfb
	s_cmp_eq_u32 s9, 3
	s_cbranch_scc0 .Lsc1_p2nfb

; #define SCAN_BAR()                                        \
;   {                                                       \
;     asm volatile("s_waitcnt lgkmcnt(0)" ::: "memory");     \
;     __builtin_amdgcn_s_barrier();                         \
;     asm volatile("" ::: "memory");                         \
;   }
; DEV void scan_item_mfma(const Params& p, int g, int item, char* smem) {
;     ...
;   for (int ci = 0; ci < NC; ++ci) {
;     const int n = dir ? NC - 1 - ci : ci;
;     const size_t tok0 = ((size_t)b * NC + n) * 64;
;     ...
;     SCAN_BAR();
;   }
.Lsc1_p3efb:
	s_mov_b32 s0, 0x50000
	s_sub_u32 s22, s22, s0
	s_subb_u32 s23, s23, 0
	s_waitcnt lgkmcnt(0)
	s_barrier
	s_lshr_b32 s8, s7, 1
	s_sub_i32 s8, s8, 2

; #define SCAN_BAR()                                        \
;   {                                                       \
;     asm volatile("s_waitcnt lgkmcnt(0)" ::: "memory");     \
;     __builtin_amdgcn_s_barrier();                         \
;     asm volatile("" ::: "memory");                         \
;   }
; DEV void scan_item_mfma(const Params& p, int g, int item, char* smem) {
;     ...
;     SCAN_BAR();
;   }
.Lsc1_p3ea:
	s_mov_b32 s0, 0x50000
	s_sub_u32 s22, s22, s0
	s_subb_u32 s23, s23, 0
	s_waitcnt lgkmcnt(0)
	s_barrier
	s_cmp_lt_u32 s9, 2
	s_cbranch_scc0 .Lsc1_w1sb
	s_waitcnt vmcnt(22)
	s_branch .Lsc1_w1eb

; #define SCAN_BAR()                                        \
;   {                                                       \
;     asm volatile("s_waitcnt lgkmcnt(0)" ::: "memory");     \
;     __builtin_amdgcn_s_barrier();                         \
;     asm volatile("" ::: "memory");                         \
;   }
; DEV void scan_item_mfma(const Params& p, int g, int item, char* smem) {
;     ...
;   for (int ci = 0; ci < NC; ++ci) {
;     const int n = dir ? NC - 1 - ci : ci;
;     const size_t tok0 = ((size_t)b * NC + n) * 64;
;     ...
;     SCAN_BAR();
;   }
.Lsc1_p3eb:
	s_mov_b32 s0, 0x50000
	s_sub_u32 s22, s22, s0
	s_subb_u32 s23, s23, 0
	s_waitcnt lgkmcnt(0)
	s_barrier
	s_sub_i32 s8, s8, 1
	s_cmp_lg_u32 s8, 0
	s_cbranch_scc1 .Lsc1_loop
	s_cmp_lt_u32 s9, 2
	s_cbranch_scc0 .Lsc1_w1sta
	s_waitcnt vmcnt(22)
	s_branch .Lsc1_w1eta

; DEV u16 f2bf(float f) { return (u16)(pack2(f, f) & 0xffffu); }
; #define SCAN_BAR()                                        \
;   {                                                       \
;     asm volatile("s_waitcnt lgkmcnt(0)" ::: "memory");     \
;     __builtin_amdgcn_s_barrier();                         \
;     asm volatile("" ::: "memory");                         \
;   }
; DEV void scan_item_mfma(const Params& p, int g, int item, char* smem) {
;     ...
;     SCAN_BAR();
;     {
;       const int nn = (ci + 1 < NC) ? (dir ? NC - 2 - ci : ci + 1) : n;
;       SCAN_ISSUE(nn);
;     }
;     __builtin_amdgcn_sched_barrier(0);
;     {
;       const int jt = wave >> 1, st = wave & 1;
;       const bool active = dir ? (st >= jt) : (st <= jt);
;       f32x16 pa;
; #pragma unroll
;       for (int i = 0; i < 16; ++i) pa[i] = 0.f;
;       if (active) {
;         bf16x8 qa[8], kb[8];
; #pragma unroll
;         for (int ks = 0; ks < 8; ++ks) {
;           qa[ks] = *(const bf16x8*)(Qs + (32 * jt + r) * 272 + ks * 32 + hh * 16);
;           kb[ks] = *(const bf16x8*)(Ks + (32 * st + r) * 272 + ks * 32 + hh * 16);
;         }
;         __builtin_amdgcn_sched_barrier(0);
;         f32x16 p1;
; #pragma unroll
;         for (int i = 0; i < 16; ++i) p1[i] = 0.f;
; #pragma unroll
;         for (int ks = 0; ks < 4; ++ks) {
;           pa = __builtin_amdgcn_mfma_f32_32x32x16_bf16(qa[2 * ks], kb[2 * ks], pa, 0, 0, 0);
;           p1 = __builtin_amdgcn_mfma_f32_32x32x16_bf16(qa[2 * ks + 1], kb[2 * ks + 1], p1, 0, 0, 0);
;         }
; #pragma unroll
;         for (int i = 0; i < 16; ++i) pa[i] += p1[i];
;       }
; #pragma unroll
;       for (int i = 0; i < 16; ++i) {
;         const int j = 32 * jt + (i & 3) + 8 * (i >> 2) + 4 * hh;
;         const int s_ = 32 * st + r;
;         const bool keep = dir ? (s_ >= j) : (s_ <= j);
;         *(u16*)(Ps + j * 144 + s_ * 2) = keep ? f2bf(pa[i]) : (u16)0;
;       }
;     }
.Lsc1_p1ota:
	s_waitcnt lgkmcnt(0)
	s_barrier
	s_cmp_eq_u32 s9, 2
	s_cbranch_scc1 .Lsc1_p2eta
	ds_read_b128 v[166:169], v240
	ds_read_b128 v[170:173], v240 offset:32
	ds_read_b128 v[174:177], v240 offset:64
	ds_read_b128 v[178:181], v240 offset:96
	ds_read_b128 v[182:185], v242 offset:17408
	ds_read_b128 v[186:189], v242 offset:17440
	ds_read_b128 v[190:193], v242 offset:17472
	ds_read_b128 v[194:197], v242 offset:17504
	s_waitcnt lgkmcnt(0)
	v_mfma_f32_32x32x16_bf16 v[144:159], v[182:185], v[166:169], 0
	v_mfma_f32_32x32x16_bf16 v[144:159], v[186:189], v[170:173], v[144:159]
	v_mfma_f32_32x32x16_bf16 v[144:159], v[190:193], v[174:177], v[144:159]
	v_mfma_f32_32x32x16_bf16 v[144:159], v[194:197], v[178:181], v[144:159]
	ds_read_b128 v[166:169], v240 offset:128
	ds_read_b128 v[170:173], v240 offset:160
	ds_read_b128 v[174:177], v240 offset:192
	ds_read_b128 v[178:181], v240 offset:224
	ds_read_b128 v[182:185], v242 offset:17536
	ds_read_b128 v[186:189], v242 offset:17568
	ds_read_b128 v[190:193], v242 offset:17600
	ds_read_b128 v[194:197], v242 offset:17632
	s_waitcnt lgkmcnt(0)
	v_mfma_f32_32x32x16_bf16 v[144:159], v[182:185], v[166:169], v[144:159]
	v_mfma_f32_32x32x16_bf16 v[144:159], v[186:189], v[170:173], v[144:159]
	v_mfma_f32_32x32x16_bf16 v[144:159], v[190:193], v[174:177], v[144:159]
	v_mfma_f32_32x32x16_bf16 v[144:159], v[194:197], v[178:181], v[144:159]
	s_nop 7
	s_nop 7
	s_cmp_eq_u32 s9, 0
	s_cbranch_scc1 .Lsc1_p2mta
	s_cmp_eq_u32 s9, 3
	s_cbranch_scc0 .Lsc1_p2nta

; #define SCAN_BAR()                                        \
;   {                                                       \
;     asm volatile("s_waitcnt lgkmcnt(0)" ::: "memory");     \
;     __builtin_amdgcn_s_barrier();                         \
;     asm volatile("" ::: "memory");                         \
;   }
; DEV void scan_item_mfma(const Params& p, int g, int item, char* smem) {
;     ...
;     SCAN_BAR();
;   }
;   if (wave < 2) {
;     u16* og = PHG + (otok + 32 * wave + 4 * hh) * 2560 + ocol + r;
.Lsc1_p3eta:
	s_mov_b32 s0, 0x50000
	s_sub_u32 s22, s22, s0
	s_subb_u32 s23, s23, 0
	s_waitcnt lgkmcnt(0)
	s_barrier
	s_cmp_lt_u32 s9, 2
	s_cbranch_scc0 .Lsc1_w1stb
	s_waitcnt vmcnt(0)
	s_branch .Lsc1_w1etb

; #define SCAN_BAR()                                        \
;   {                                                       \
;     asm volatile("s_waitcnt lgkmcnt(0)" ::: "memory");     \
;     __builtin_amdgcn_s_barrier();                         \
;     asm volatile("" ::: "memory");                         \
;   }
; DEV void scan_item_mfma(const Params& p, int g, int item, char* smem) {
;     ...
;     SCAN_BAR();
;   }
;   if (wave < 2) {
;     u16* og = PHG + (otok + 32 * wave + 4 * hh) * 2560 + ocol + r;
; #pragma unroll
;     for (int i = 0; i < 8; ++i) {
;       og[(size_t)(((2 * i) & 3) + 8 * ((2 * i) >> 2)) * 2560] = (u16)(opk[i] & 0xffffu);
;       og[(size_t)(((2 * i + 1) & 3) + 8 * ((2 * i + 1) >> 2)) * 2560] = (u16)(opk[i] >> 16);
;     }
;   }
;     ...
; }
; DEV void phase_p2_naive(const Params& p, int g, char* hsm) {
;     ...
;   if ((int)blockIdx.x * 2 < nscan) scan_item_mfma(p, g, blockIdx.x * 2 + half, hsm);
.Lsc1_p3etb:
	s_mov_b32 s0, 0x50000
	s_sub_u32 s22, s22, s0
	s_subb_u32 s23, s23, 0
	s_waitcnt lgkmcnt(0)
	s_barrier
.Lscan_done:
	s_waitcnt vmcnt(0)
	v_mov_b32_e32 v207, 0x25810
	v_mov_b32_e32 v208, 0x2000
	v_mov_b32_e32 v209, 0x3000
	v_mov_b32_e32 v210, 0x1000
	v_mov_b32_e32 v211, 0x4000
	v_mov_b32_e32 v212, 0x358637bd
	v_mov_b32_e32 v213, 0x41b17218
	v_mov_b32_e32 v214, 2
	v_mov_b32_e32 v215, 0x1400
	v_mov_b32_e32 v216, 0x9000
	v_mov_b32_e32 v218, 0
	v_mov_b32_e32 v219, 0
	v_mov_b32_e32 v220, 0
	v_mov_b32_e32 v221, 0
	v_readlane_b32 s0, v160, 0
	v_readlane_b32 s1, v160, 1
	v_readlane_b32 s2, v160, 2
	v_readlane_b32 s3, v160, 3
	v_readlane_b32 s4, v160, 4
	v_readlane_b32 s5, v160, 5
	v_readlane_b32 s6, v160, 6
	v_readlane_b32 s7, v160, 7
	v_readlane_b32 s8, v160, 8
	v_readlane_b32 s9, v160, 9
	v_readlane_b32 s10, v160, 10
	v_readlane_b32 s11, v160, 11
	v_readlane_b32 s12, v160, 12
	v_readlane_b32 s13, v160, 13
	v_readlane_b32 s14, v160, 14
	v_readlane_b32 s15, v160, 15
	v_readlane_b32 s16, v160, 16
	v_readlane_b32 s17, v160, 17
	v_readlane_b32 s18, v160, 18
	v_readlane_b32 s19, v160, 19
	v_readlane_b32 s20, v160, 20
	v_readlane_b32 s21, v160, 21
	v_readlane_b32 s22, v160, 22
	v_readlane_b32 s23, v160, 23
	v_readlane_b32 s24, v160, 24
	v_readlane_b32 s25, v160, 25
	v_readlane_b32 s26, v160, 26
	v_readlane_b32 s27, v160, 27
	v_readlane_b32 s28, v160, 28
	v_readlane_b32 s29, v160, 29
	v_readlane_b32 s30, v160, 30
	v_readlane_b32 s31, v160, 31
	v_readlane_b32 s33, v160, 33
	v_readlane_b32 s34, v160, 34
	v_readlane_b32 s35, v160, 35
	v_readlane_b32 s36, v160, 36
	v_readlane_b32 s37, v160, 37
	v_readlane_b32 s38, v160, 38
	v_readlane_b32 s39, v160, 39
	v_readlane_b32 s40, v160, 40
	v_readlane_b32 s41, v160, 41
	v_readlane_b32 s42, v160, 42
	v_readlane_b32 s43, v160, 43
	v_readlane_b32 s44, v160, 44
	v_readlane_b32 s45, v160, 45
	v_readlane_b32 s46, v160, 46
	v_readlane_b32 s47, v160, 47
	v_readlane_b32 s48, v160, 48
	v_readlane_b32 s49, v160, 49
	v_readlane_b32 s50, v160, 50
	v_readlane_b32 s51, v160, 51
	v_readlane_b32 s52, v160, 52
	v_readlane_b32 s53, v160, 53
	v_readlane_b32 s54, v160, 54
	v_readlane_b32 s55, v160, 55
	v_readlane_b32 s56, v160, 56
	v_readlane_b32 s57, v160, 57
	v_readlane_b32 s58, v160, 58
	v_readlane_b32 s59, v160, 59
	v_readlane_b32 s60, v160, 60
	v_readlane_b32 s61, v160, 61
	v_readlane_b32 s62, v160, 62
	v_readlane_b32 s63, v160, 63
	v_readlane_b32 s64, v161, 0
	v_readlane_b32 s65, v161, 1
	v_readlane_b32 s66, v161, 2
	v_readlane_b32 s67, v161, 3
	v_readlane_b32 s68, v161, 4
	v_readlane_b32 s69, v161, 5
	v_readlane_b32 s70, v161, 6
	v_readlane_b32 s71, v161, 7
	v_readlane_b32 s72, v161, 8
	v_readlane_b32 s73, v161, 9

; template <class AL, class BL>
; DEV void gemm_mainloop(Acc& acc, const AL& al, const BL& bl, int m0, int n0, int kbeg, int kend, char* lds) {
;   const int tid = tidx_full();
;   const int wave = tid >> 6, lane = tid & 63;
;   const int wm = (wave >> 2) * 128, wn = (wave & 3) * 64;
;   const int lr = lane & 31, lh = lane >> 5;
;   const int nk = (kend - kbeg) / BK;
;   R4 a0 = al.load(tid, m0, kbeg);
;   R4 b0 = bl.load(tid, n0, kbeg);
;   __syncthreads();
;   al.store(tid, lds, a0);
;   bl.store(tid, lds + TILE_BYTES, b0);
;   a0 = al.load(tid, m0, kbeg + BK);
;   b0 = bl.load(tid, n0, kbeg + BK);
;   __syncthreads();
; DEV void phase_ff2(const Params& p, int g, char* smem) {
;     ...
;   for (int iter = 0;; ++iter) {
;     int mt, nt;
;     if (!tile_map(iter, 128, 4, mt, nt)) break;
;     const int m0 = mt * 256, n0 = nt * 256;
;     Acc acc;
;     acc_zero(acc);
;     RowLoader al{AB, 4096}, bl{W, 4096};
;     gemm_mainloop(acc, al, bl, m0, n0, 0, 4096, smem);
.LBB0_1192:
	s_lshl_b32 s3, s5, 8
	s_lshl_b32 s2, s6, 8
	v_readlane_b32 s0, v251, 30
	v_readlane_b32 s1, v251, 31
	s_mov_b64 s[6:7], s[74:75]
	v_lshrrev_b32_e32 v145, 6, v202
	v_and_b32_e32 v144, 63, v202
	s_nop 0
	v_readfirstlane_b32 s8, v145
	v_lshrrev_b32_e32 v146, 3, v144
	v_lshl_add_u32 v146, v145, 5, v146
	v_and_b32_e32 v147, 7, v144
	v_lshrrev_b32_e32 v128, 4, v144
	v_xor_b32_e32 v147, v128, v147
	v_lshlrev_b32_e32 v147, 4, v147
	s_lshl_b32 s8, s8, 12
	v_add_u32_e32 v128, s3, v146
	v_lshlrev_b32_e32 v128, 13, v128
	v_add_u32_e32 v128, v128, v147
	v_add_u32_e32 v129, 0x10000, v128
	v_add_u32_e32 v130, 0x20000, v128
	v_add_u32_e32 v131, 0x30000, v128
	v_xor_b32_e32 v129, 0x40, v129
	v_xor_b32_e32 v131, 0x40, v131
	v_add_u32_e32 v132, s2, v146
	v_lshlrev_b32_e32 v132, 13, v132
	v_add_u32_e32 v132, v132, v147
	v_add_u32_e32 v133, 0x10000, v132
	v_add_u32_e32 v134, 0x20000, v132
	v_add_u32_e32 v135, 0x30000, v132
	v_xor_b32_e32 v133, 0x40, v133
	v_xor_b32_e32 v135, 0x40, v135
	v_lshrrev_b32_e32 v146, 1, v144
	v_and_b32_e32 v146, 7, v146
	v_lshrrev_b32_e32 v147, 5, v144
	v_xor_b32_e32 v146, v146, v147
	v_lshlrev_b32_e32 v146, 4, v146
	v_and_b32_e32 v147, 31, v144
	v_lshlrev_b32_e32 v147, 7, v147
	v_lshrrev_b32_e32 v136, 2, v145
	v_lshl_add_u32 v136, v136, 14, v147
	v_and_b32_e32 v140, 3, v145
	v_lshl_add_u32 v140, v140, 13, v147
	v_add_u32_e32 v140, 0x10000, v140
	v_xor_b32_e32 v139, 0x60, v146
	v_add_u32_e32 v139, v136, v139
	v_xor_b32_e32 v138, 0x40, v146
	v_add_u32_e32 v138, v136, v138
	v_xor_b32_e32 v137, 0x20, v146
	v_add_u32_e32 v137, v136, v137
	v_add_u32_e32 v136, v136, v146
	v_xor_b32_e32 v143, 0x60, v146
	v_add_u32_e32 v143, v140, v143
	v_xor_b32_e32 v142, 0x40, v146
	v_add_u32_e32 v142, v140, v142
	v_xor_b32_e32 v141, 0x20, v146
	v_add_u32_e32 v141, v140, v141
	v_add_u32_e32 v140, v140, v146
	v_mov_b32_e32 v0, 0
	v_mov_b32_e32 v1, 0
	v_mov_b64_e32 v[2:3], v[0:1]
	v_mov_b64_e32 v[4:5], v[0:1]
	v_mov_b64_e32 v[6:7], v[0:1]
	v_mov_b64_e32 v[8:9], v[0:1]
	v_mov_b64_e32 v[10:11], v[0:1]
	v_mov_b64_e32 v[12:13], v[0:1]
	v_mov_b64_e32 v[14:15], v[0:1]
	v_mov_b64_e32 v[16:17], v[0:1]
	v_mov_b64_e32 v[18:19], v[0:1]
	v_mov_b64_e32 v[20:21], v[0:1]
	v_mov_b64_e32 v[22:23], v[0:1]
	v_mov_b64_e32 v[24:25], v[0:1]
	v_mov_b64_e32 v[26:27], v[0:1]
	v_mov_b64_e32 v[28:29], v[0:1]
	v_mov_b64_e32 v[30:31], v[0:1]
	v_mov_b64_e32 v[32:33], v[0:1]
	v_mov_b64_e32 v[34:35], v[0:1]
	v_mov_b64_e32 v[36:37], v[0:1]
	v_mov_b64_e32 v[38:39], v[0:1]
	v_mov_b64_e32 v[40:41], v[0:1]
	v_mov_b64_e32 v[42:43], v[0:1]
	v_mov_b64_e32 v[44:45], v[0:1]
	v_mov_b64_e32 v[46:47], v[0:1]
	v_mov_b64_e32 v[48:49], v[0:1]
	v_mov_b64_e32 v[50:51], v[0:1]
	v_mov_b64_e32 v[52:53], v[0:1]
	v_mov_b64_e32 v[54:55], v[0:1]
	v_mov_b64_e32 v[56:57], v[0:1]
	v_mov_b64_e32 v[58:59], v[0:1]
	v_mov_b64_e32 v[60:61], v[0:1]
	v_mov_b64_e32 v[62:63], v[0:1]
	v_mov_b64_e32 v[64:65], v[0:1]
	v_mov_b64_e32 v[66:67], v[0:1]
	v_mov_b64_e32 v[68:69], v[0:1]
	v_mov_b64_e32 v[70:71], v[0:1]
	v_mov_b64_e32 v[72:73], v[0:1]
	v_mov_b64_e32 v[74:75], v[0:1]
	v_mov_b64_e32 v[76:77], v[0:1]
	v_mov_b64_e32 v[78:79], v[0:1]
	v_mov_b64_e32 v[80:81], v[0:1]
	v_mov_b64_e32 v[82:83], v[0:1]
	v_mov_b64_e32 v[84:85], v[0:1]
	v_mov_b64_e32 v[86:87], v[0:1]
	v_mov_b64_e32 v[88:89], v[0:1]
	v_mov_b64_e32 v[90:91], v[0:1]
	v_mov_b64_e32 v[92:93], v[0:1]
	v_mov_b64_e32 v[94:95], v[0:1]
	v_mov_b64_e32 v[96:97], v[0:1]
	v_mov_b64_e32 v[98:99], v[0:1]
	v_mov_b64_e32 v[100:101], v[0:1]
	v_mov_b64_e32 v[102:103], v[0:1]
	v_mov_b64_e32 v[104:105], v[0:1]
	v_mov_b64_e32 v[106:107], v[0:1]
	v_mov_b64_e32 v[108:109], v[0:1]
	v_mov_b64_e32 v[110:111], v[0:1]
	v_mov_b64_e32 v[112:113], v[0:1]
	v_mov_b64_e32 v[114:115], v[0:1]
	v_mov_b64_e32 v[116:117], v[0:1]
	v_mov_b64_e32 v[118:119], v[0:1]
	v_mov_b64_e32 v[120:121], v[0:1]
	v_mov_b64_e32 v[122:123], v[0:1]
	v_mov_b64_e32 v[124:125], v[0:1]
	v_mov_b64_e32 v[126:127], v[0:1]
	s_add_u32 m0, s8, 0x0
	s_nop 0
	global_load_lds_dwordx4 v128, s[6:7]
	s_add_u32 m0, m0, 0x400
	s_nop 0
	global_load_lds_dwordx4 v129, s[6:7]
	s_add_u32 m0, m0, 0x400
	s_nop 0
	global_load_lds_dwordx4 v130, s[6:7]
	s_add_u32 m0, m0, 0x400
	s_nop 0
	global_load_lds_dwordx4 v131, s[6:7]
	s_add_u32 m0, s8, 0x10000
	s_nop 0
	global_load_lds_dwordx4 v132, s[0:1]
	s_add_u32 m0, m0, 0x400
	s_nop 0
	global_load_lds_dwordx4 v133, s[0:1]
	s_add_u32 m0, m0, 0x400
	s_nop 0
	global_load_lds_dwordx4 v134, s[0:1]
	s_add_u32 m0, m0, 0x400
	s_nop 0
	global_load_lds_dwordx4 v135, s[0:1]
	s_add_u32 s6, s6, 0x80
	s_addc_u32 s7, s7, 0
	s_add_u32 s0, s0, 0x80
	s_addc_u32 s1, s1, 0
	s_mov_b32 s5, 0
	s_waitcnt vmcnt(0)
	s_barrier
; template <class AL, class BL>
; DEV void gemm_ktile(Acc& acc, const char* A, const char* B, int wm, int wn, int lr, int lh, const AL& al, const BL& bl,
;                     int tid, int m0, int n0, int knext, char* nxt, R4& ra, R4& rb) {
;   bf16x8 a[2][4], b[2][2];
;   const char* pa = A + (wm + lr) * LDSROW + lh * 16;
;   const char* pb = B + (wn + lr) * LDSROW + lh * 16;
; #pragma unroll
;   for (int i = 0; i < 4; ++i) a[0][i] = *(const bf16x8*)(pa + 32 * i * LDSROW);
; #pragma unroll
;   for (int j = 0; j < 2; ++j) b[0][j] = *(const bf16x8*)(pb + 32 * j * LDSROW);
; #pragma unroll
;   for (int ks = 0; ks < 4; ++ks) {
;     const int cur = ks & 1, nx = cur ^ 1;
;     if (ks < 3) {
; #pragma unroll
;       for (int i = 0; i < 4; ++i) a[nx][i] = *(const bf16x8*)(pa + 32 * i * LDSROW + (ks + 1) * 32);
; #pragma unroll
;       for (int j = 0; j < 2; ++j) b[nx][j] = *(const bf16x8*)(pb + 32 * j * LDSROW + (ks + 1) * 32);
;     }
;     __builtin_amdgcn_sched_barrier(0);
; #pragma unroll
;     for (int i = 0; i < 4; ++i)
; #pragma unroll
;       for (int j = 0; j < 2; ++j)
;         acc[i][j] = __builtin_amdgcn_mfma_f32_32x32x16_bf16(a[cur][i], b[cur][j], acc[i][j], 0, 0, 0);
;     __builtin_amdgcn_sched_barrier(0);
;     if (ks == 1) {
;       al.store(tid, nxt, ra);
;       bl.store(tid, nxt + TILE_BYTES, rb);
;       __builtin_amdgcn_sched_barrier(0);
;       ra = al.load(tid, m0, knext);
;       rb = bl.load(tid, n0, knext);
;       __builtin_amdgcn_sched_barrier(0);
;     }
;   }
; template <class AL, class BL>
; DEV void gemm_mainloop(Acc& acc, const AL& al, const BL& bl, int m0, int n0, int kbeg, int kend, char* lds) {
;     ...
;   for (int kt = 0; kt < nk; ++kt) {
;     const char* cur = lds + (kt & 1) * 2 * TILE_BYTES;
;     char* nxt = lds + ((kt + 1) & 1) * 2 * TILE_BYTES;
;     const int t2 = (kt + 2 < nk) ? kt + 2 : nk - 1;
;     __builtin_amdgcn_sched_barrier(0);
;     gemm_ktile(acc, cur, cur + TILE_BYTES, wm, wn, lr, lh, al, bl, tid, m0, n0, kbeg + t2 * BK, nxt, a0, b0);
;     __builtin_amdgcn_sched_barrier(0);
;     __syncthreads();
;   }
.Lff2_kloop:
	s_add_u32 m0, s8, 0x8000
	s_nop 0
	global_load_lds_dwordx4 v128, s[6:7]
	s_add_u32 m0, m0, 0x400
	s_nop 0
	global_load_lds_dwordx4 v129, s[6:7]
	s_add_u32 m0, m0, 0x400
	s_nop 0
	global_load_lds_dwordx4 v130, s[6:7]
	s_add_u32 m0, m0, 0x400
	s_nop 0
	global_load_lds_dwordx4 v131, s[6:7]
	s_add_u32 m0, s8, 0x18000
	s_nop 0
	global_load_lds_dwordx4 v132, s[0:1]
	s_add_u32 m0, m0, 0x400
	s_nop 0
	global_load_lds_dwordx4 v133, s[0:1]
	s_add_u32 m0, m0, 0x400
	s_nop 0
	global_load_lds_dwordx4 v134, s[0:1]
	s_add_u32 m0, m0, 0x400
	s_nop 0
	global_load_lds_dwordx4 v135, s[0:1]
	s_add_u32 s6, s6, 0x80
	s_addc_u32 s7, s7, 0
	s_add_u32 s0, s0, 0x80
	s_addc_u32 s1, s1, 0
	ds_read_b128 v[174:177], v136
	ds_read_b128 v[178:181], v137
	ds_read_b128 v[182:185], v136 offset:4096
	ds_read_b128 v[186:189], v137 offset:4096
	ds_read_b128 v[190:193], v136 offset:8192
	ds_read_b128 v[194:197], v137 offset:8192
	ds_read_b128 v[198:201], v136 offset:12288
	ds_read_b128 v[222:225], v137 offset:12288
	ds_read_b128 v[226:229], v140
	ds_read_b128 v[230:233], v141
	ds_read_b128 v[234:237], v140 offset:4096
	ds_read_b128 v[238:241], v141 offset:4096
	s_waitcnt lgkmcnt(3)
	v_mfma_f32_32x32x16_bf16 v[112:127], v[226:229], v[174:177], v[112:127]
	s_waitcnt lgkmcnt(1)
	v_mfma_f32_32x32x16_bf16 v[96:111], v[234:237], v[174:177], v[96:111]
	v_mfma_f32_32x32x16_bf16 v[80:95], v[226:229], v[182:185], v[80:95]
	v_mfma_f32_32x32x16_bf16 v[64:79], v[234:237], v[182:185], v[64:79]
	v_mfma_f32_32x32x16_bf16 v[48:63], v[226:229], v[190:193], v[48:63]
	v_mfma_f32_32x32x16_bf16 v[32:47], v[234:237], v[190:193], v[32:47]
	v_mfma_f32_32x32x16_bf16 v[16:31], v[226:229], v[198:201], v[16:31]
	v_mfma_f32_32x32x16_bf16 v[0:15], v[234:237], v[198:201], v[0:15]
	ds_read_b128 v[174:177], v138
	ds_read_b128 v[182:185], v138 offset:4096
	ds_read_b128 v[190:193], v138 offset:8192
	ds_read_b128 v[198:201], v138 offset:12288
	ds_read_b128 v[226:229], v142
	ds_read_b128 v[234:237], v142 offset:4096
	v_mfma_f32_32x32x16_bf16 v[112:127], v[230:233], v[178:181], v[112:127]
	s_waitcnt lgkmcnt(6)
	v_mfma_f32_32x32x16_bf16 v[96:111], v[238:241], v[178:181], v[96:111]
	v_mfma_f32_32x32x16_bf16 v[80:95], v[230:233], v[186:189], v[80:95]
	v_mfma_f32_32x32x16_bf16 v[64:79], v[238:241], v[186:189], v[64:79]
	v_mfma_f32_32x32x16_bf16 v[48:63], v[230:233], v[194:197], v[48:63]
	v_mfma_f32_32x32x16_bf16 v[32:47], v[238:241], v[194:197], v[32:47]
	v_mfma_f32_32x32x16_bf16 v[16:31], v[230:233], v[222:225], v[16:31]
	v_mfma_f32_32x32x16_bf16 v[0:15], v[238:241], v[222:225], v[0:15]
	ds_read_b128 v[178:181], v139
	ds_read_b128 v[186:189], v139 offset:4096
	ds_read_b128 v[194:197], v139 offset:8192
	ds_read_b128 v[222:225], v139 offset:12288
	ds_read_b128 v[230:233], v143
	ds_read_b128 v[238:241], v143 offset:4096
	s_waitcnt lgkmcnt(6)
	v_mfma_f32_32x32x16_bf16 v[112:127], v[226:229], v[174:177], v[112:127]
	v_mfma_f32_32x32x16_bf16 v[96:111], v[234:237], v[174:177], v[96:111]
	v_mfma_f32_32x32x16_bf16 v[80:95], v[226:229], v[182:185], v[80:95]
	v_mfma_f32_32x32x16_bf16 v[64:79], v[234:237], v[182:185], v[64:79]
	v_mfma_f32_32x32x16_bf16 v[48:63], v[226:229], v[190:193], v[48:63]
	v_mfma_f32_32x32x16_bf16 v[32:47], v[234:237], v[190:193], v[32:47]
	v_mfma_f32_32x32x16_bf16 v[16:31], v[226:229], v[198:201], v[16:31]
	v_mfma_f32_32x32x16_bf16 v[0:15], v[234:237], v[198:201], v[0:15]
	s_waitcnt lgkmcnt(1)
	v_mfma_f32_32x32x16_bf16 v[112:127], v[230:233], v[178:181], v[112:127]
	s_waitcnt lgkmcnt(0)
	v_mfma_f32_32x32x16_bf16 v[96:111], v[238:241], v[178:181], v[96:111]
	v_mfma_f32_32x32x16_bf16 v[80:95], v[230:233], v[186:189], v[80:95]
	v_mfma_f32_32x32x16_bf16 v[64:79], v[238:241], v[186:189], v[64:79]
	v_mfma_f32_32x32x16_bf16 v[48:63], v[230:233], v[194:197], v[48:63]
	v_mfma_f32_32x32x16_bf16 v[32:47], v[238:241], v[194:197], v[32:47]
	v_mfma_f32_32x32x16_bf16 v[16:31], v[230:233], v[222:225], v[16:31]
	v_mfma_f32_32x32x16_bf16 v[0:15], v[238:241], v[222:225], v[0:15]
	s_waitcnt vmcnt(0)
	s_barrier
	s_cmp_eq_u32 s5, 31
	s_cbranch_scc1 .Lff2_skipdma
	s_add_u32 m0, s8, 0x0
	s_nop 0
	global_load_lds_dwordx4 v128, s[6:7]
	s_add_u32 m0, m0, 0x400
	s_nop 0
	global_load_lds_dwordx4 v129, s[6:7]
	s_add_u32 m0, m0, 0x400
	s_nop 0
	global_load_lds_dwordx4 v130, s[6:7]
	s_add_u32 m0, m0, 0x400
	s_nop 0
	global_load_lds_dwordx4 v131, s[6:7]
	s_add_u32 m0, s8, 0x10000
	s_nop 0
	global_load_lds_dwordx4 v132, s[0:1]
	s_add_u32 m0, m0, 0x400
	s_nop 0
	global_load_lds_dwordx4 v133, s[0:1]
	s_add_u32 m0, m0, 0x400
	s_nop 0
	global_load_lds_dwordx4 v134, s[0:1]
	s_add_u32 m0, m0, 0x400
	s_nop 0
	global_load_lds_dwordx4 v135, s[0:1]
	s_add_u32 s6, s6, 0x80
	s_addc_u32 s7, s7, 0
	s_add_u32 s0, s0, 0x80
	s_addc_u32 s1, s1, 0
; template <class AL, class BL>
; DEV void gemm_ktile(Acc& acc, const char* A, const char* B, int wm, int wn, int lr, int lh, const AL& al, const BL& bl,
;                     int tid, int m0, int n0, int knext, char* nxt, R4& ra, R4& rb) {
;   bf16x8 a[2][4], b[2][2];
;   const char* pa = A + (wm + lr) * LDSROW + lh * 16;
;   const char* pb = B + (wn + lr) * LDSROW + lh * 16;
; #pragma unroll
;   for (int i = 0; i < 4; ++i) a[0][i] = *(const bf16x8*)(pa + 32 * i * LDSROW);
; #pragma unroll
;   for (int j = 0; j < 2; ++j) b[0][j] = *(const bf16x8*)(pb + 32 * j * LDSROW);
; #pragma unroll
;   for (int ks = 0; ks < 4; ++ks) {
;     const int cur = ks & 1, nx = cur ^ 1;
;     if (ks < 3) {
; #pragma unroll
;       for (int i = 0; i < 4; ++i) a[nx][i] = *(const bf16x8*)(pa + 32 * i * LDSROW + (ks + 1) * 32);
; #pragma unroll
;       for (int j = 0; j < 2; ++j) b[nx][j] = *(const bf16x8*)(pb + 32 * j * LDSROW + (ks + 1) * 32);
;     }
;     __builtin_amdgcn_sched_barrier(0);
; #pragma unroll
;     for (int i = 0; i < 4; ++i)
; #pragma unroll
;       for (int j = 0; j < 2; ++j)
;         acc[i][j] = __builtin_amdgcn_mfma_f32_32x32x16_bf16(a[cur][i], b[cur][j], acc[i][j], 0, 0, 0);
;     __builtin_amdgcn_sched_barrier(0);
;     if (ks == 1) {
;       al.store(tid, nxt, ra);
;       bl.store(tid, nxt + TILE_BYTES, rb);
;       __builtin_amdgcn_sched_barrier(0);
;       ra = al.load(tid, m0, knext);
;       rb = bl.load(tid, n0, knext);
;       __builtin_amdgcn_sched_barrier(0);
;     }
;   }
; DEV void phase_ff2(const Params& p, int g, char* smem) {
;     ...
;     const float* gt = mod + (size_t)(bg0 + m0 / L) * DIN + 5120;
;     acc_foreach(acc, m0, n0, [&](int m, int n, float& v) { X1[(size_t)m * D + n] += gt[n] * v; });
.Lff2_skipdma:
	ds_read_b128 v[174:177], v136 offset:32768
	ds_read_b128 v[178:181], v137 offset:32768
	ds_read_b128 v[182:185], v136 offset:36864
	ds_read_b128 v[186:189], v137 offset:36864
	ds_read_b128 v[190:193], v136 offset:40960
	ds_read_b128 v[194:197], v137 offset:40960
	ds_read_b128 v[198:201], v136 offset:45056
	ds_read_b128 v[222:225], v137 offset:45056
	ds_read_b128 v[226:229], v140 offset:32768
	ds_read_b128 v[230:233], v141 offset:32768
	ds_read_b128 v[234:237], v140 offset:36864
	ds_read_b128 v[238:241], v141 offset:36864
	s_waitcnt lgkmcnt(3)
	v_mfma_f32_32x32x16_bf16 v[112:127], v[226:229], v[174:177], v[112:127]
	s_waitcnt lgkmcnt(1)
	v_mfma_f32_32x32x16_bf16 v[96:111], v[234:237], v[174:177], v[96:111]
	v_mfma_f32_32x32x16_bf16 v[80:95], v[226:229], v[182:185], v[80:95]
	v_mfma_f32_32x32x16_bf16 v[64:79], v[234:237], v[182:185], v[64:79]
	v_mfma_f32_32x32x16_bf16 v[48:63], v[226:229], v[190:193], v[48:63]
	v_mfma_f32_32x32x16_bf16 v[32:47], v[234:237], v[190:193], v[32:47]
	v_mfma_f32_32x32x16_bf16 v[16:31], v[226:229], v[198:201], v[16:31]
	v_mfma_f32_32x32x16_bf16 v[0:15], v[234:237], v[198:201], v[0:15]
	ds_read_b128 v[174:177], v138 offset:32768
	ds_read_b128 v[182:185], v138 offset:36864
	ds_read_b128 v[190:193], v138 offset:40960
	ds_read_b128 v[198:201], v138 offset:45056
	ds_read_b128 v[226:229], v142 offset:32768
	ds_read_b128 v[234:237], v142 offset:36864
	v_mfma_f32_32x32x16_bf16 v[112:127], v[230:233], v[178:181], v[112:127]
	s_waitcnt lgkmcnt(6)
	v_mfma_f32_32x32x16_bf16 v[96:111], v[238:241], v[178:181], v[96:111]
	v_mfma_f32_32x32x16_bf16 v[80:95], v[230:233], v[186:189], v[80:95]
	v_mfma_f32_32x32x16_bf16 v[64:79], v[238:241], v[186:189], v[64:79]
	v_mfma_f32_32x32x16_bf16 v[48:63], v[230:233], v[194:197], v[48:63]
	v_mfma_f32_32x32x16_bf16 v[32:47], v[238:241], v[194:197], v[32:47]
	v_mfma_f32_32x32x16_bf16 v[16:31], v[230:233], v[222:225], v[16:31]
	v_mfma_f32_32x32x16_bf16 v[0:15], v[238:241], v[222:225], v[0:15]
	ds_read_b128 v[178:181], v139 offset:32768
	ds_read_b128 v[186:189], v139 offset:36864
	ds_read_b128 v[194:197], v139 offset:40960
	ds_read_b128 v[222:225], v139 offset:45056
	ds_read_b128 v[230:233], v143 offset:32768
	ds_read_b128 v[238:241], v143 offset:36864
	s_waitcnt lgkmcnt(6)
	v_mfma_f32_32x32x16_bf16 v[112:127], v[226:229], v[174:177], v[112:127]
	v_mfma_f32_32x32x16_bf16 v[96:111], v[234:237], v[174:177], v[96:111]
	v_mfma_f32_32x32x16_bf16 v[80:95], v[226:229], v[182:185], v[80:95]
	v_mfma_f32_32x32x16_bf16 v[64:79], v[234:237], v[182:185], v[64:79]
	v_mfma_f32_32x32x16_bf16 v[48:63], v[226:229], v[190:193], v[48:63]
	v_mfma_f32_32x32x16_bf16 v[32:47], v[234:237], v[190:193], v[32:47]
	v_mfma_f32_32x32x16_bf16 v[16:31], v[226:229], v[198:201], v[16:31]
	v_mfma_f32_32x32x16_bf16 v[0:15], v[234:237], v[198:201], v[0:15]
	s_waitcnt lgkmcnt(1)
	v_mfma_f32_32x32x16_bf16 v[112:127], v[230:233], v[178:181], v[112:127]
	s_waitcnt lgkmcnt(0)
	v_mfma_f32_32x32x16_bf16 v[96:111], v[238:241], v[178:181], v[96:111]
	v_mfma_f32_32x32x16_bf16 v[80:95], v[230:233], v[186:189], v[80:95]
	v_mfma_f32_32x32x16_bf16 v[64:79], v[238:241], v[186:189], v[64:79]
	v_mfma_f32_32x32x16_bf16 v[48:63], v[230:233], v[194:197], v[48:63]
	v_mfma_f32_32x32x16_bf16 v[32:47], v[238:241], v[194:197], v[32:47]
	v_mfma_f32_32x32x16_bf16 v[16:31], v[230:233], v[222:225], v[16:31]
	v_mfma_f32_32x32x16_bf16 v[0:15], v[238:241], v[222:225], v[0:15]
	s_add_i32 s5, s5, 1
	s_waitcnt vmcnt(0)
	s_cmp_lg_u32 s5, 32
	s_barrier
	s_cbranch_scc1 .Lff2_kloop
	s_abs_i32 s1, s3
	v_readlane_b32 s5, v252, 17
	s_mul_hi_u32 s5, s1, s5
	v_readlane_b32 s8, v252, 16
	s_mul_i32 s6, s5, s8
	s_sub_i32 s1, s1, s6
	s_ashr_i32 s0, s3, 31
	s_add_i32 s6, s5, 1
	s_sub_i32 s7, s1, s8
	s_cmp_ge_u32 s1, s8
	s_cselect_b32 s5, s6, s5
	s_cselect_b32 s1, s7, s1
	s_add_i32 s6, s5, 1
	s_cmp_ge_u32 s1, s8
	s_cselect_b32 s1, s6, s5
	s_xor_b32 s1, s1, s0
	s_sub_i32 s0, s1, s0
	s_add_i32 s0, s0, s16
	s_mul_hi_i32 s1, s0, 0x6000
	s_mulk_i32 s0, 0x6000
	s_add_u32 s0, s88, s0
	s_addc_u32 s1, s89, s1
	s_add_u32 s0, s0, 0x2005000
	s_addc_u32 s1, s1, 0
	s_waitcnt vmcnt(0)
	s_nop 7
	s_nop 7
	s_nop 3
	v_and_b32_e32 v160, 63, v202
	v_lshrrev_b32_e32 v161, 6, v202
	v_and_b32_e32 v164, 3, v161
	v_lshlrev_b32_e32 v164, 13, v164
	v_add_u32_e32 v164, 0x8000, v164
	v_lshrrev_b32_e32 v160, 2, v161
	v_lshl_add_u32 v164, v160, 16, v164
	v_and_b32_e32 v160, 63, v202
	v_lshrrev_b32_e32 v166, 4, v160
	v_and_b32_e32 v167, 15, v160
	v_lshrrev_b32_e32 v182, 2, v161
	v_lshl_add_u32 v182, v182, 7, v166
	v_add_u32_e32 v182, s3, v182
	v_lshlrev_b32_e32 v182, 12, v182
	v_and_b32_e32 v184, 3, v161
	v_lshl_add_u32 v184, v184, 4, v167
	v_lshlrev_b32_e32 v184, 4, v184
	s_lshl_b32 s100, s2, 2
	v_add_u32_e32 v184, s100, v184
	v_add_u32_e32 v182, v182, v184
	v_mov_b32_e32 v183, v182
	global_load_dwordx4 v[128:131], v182, s[64:65]
	v_add_u32_e32 v182, 0x4000, v182
	global_load_dwordx4 v[132:135], v182, s[64:65]
	v_add_u32_e32 v182, 0x4000, v182
	global_load_dwordx4 v[136:139], v182, s[64:65]
	v_add_u32_e32 v182, 0x4000, v182
	global_load_dwordx4 v[140:143], v182, s[64:65]
	v_add_u32_e32 v182, 0x4000, v182
	global_load_dwordx4 v[144:147], v182, s[64:65]
	v_add_u32_e32 v182, 0x4000, v182
	global_load_dwordx4 v[148:151], v182, s[64:65]
	v_add_u32_e32 v182, 0x4000, v182
	global_load_dwordx4 v[152:155], v182, s[64:65]
	v_add_u32_e32 v182, 0x4000, v182
	global_load_dwordx4 v[156:159], v182, s[64:65]
	v_add_u32_e32 v182, 0x4000, v182
	global_load_dwordx4 v[188:191], v182, s[64:65]
	v_add_u32_e32 v182, 0x4000, v182
	global_load_dwordx4 v[192:195], v182, s[64:65]
	v_add_u32_e32 v182, 0x4000, v182
; template <class F>
; DEV void acc_foreach(Acc& acc, int m0, int n0, F f) {
;   asm volatile("s_nop 7\n\ts_nop 7\n\ts_nop 3" ::: "memory");
;   const int tid = tidx_full();
;   const int wave = tid >> 6, lane = tid & 63;
;   const int wm = (wave >> 2) * 128, wn = (wave & 3) * 64;
;   const int lr = lane & 31, lh = lane >> 5;
; #pragma unroll
;   for (int i = 0; i < 4; ++i)
; #pragma unroll
;     for (int j = 0; j < 2; ++j)
; #pragma unroll
;       for (int r = 0; r < 16; ++r) {
;         const int m = m0 + wm + 32 * i + (r & 3) + 8 * (r >> 2) + 4 * lh;
;         const int n = n0 + wn + 32 * j + lr;
;         float v = acc[i][j][r];
;         f(m, n, v);
;         acc[i][j][r] = v;
;       }
; }
; DEV void phase_ff2(const Params& p, int g, char* smem) {
;     ...
;     acc_foreach(acc, m0, n0, [&](int m, int n, float& v) { X1[(size_t)m * D + n] += gt[n] * v; });
	global_load_dwordx4 v[196:199], v182, s[64:65]
	v_add_u32_e32 v182, 0x4000, v182
	global_load_dwordx4 v[222:225], v182, s[64:65]
	v_add_u32_e32 v182, 0x4000, v182
	global_load_dwordx4 v[226:229], v182, s[64:65]
	v_add_u32_e32 v182, 0x4000, v182
	global_load_dwordx4 v[230:233], v182, s[64:65]
	v_add_u32_e32 v182, 0x4000, v182
	global_load_dwordx4 v[234:237], v182, s[64:65]
	v_add_u32_e32 v182, 0x4000, v182
	global_load_dwordx4 v[238:241], v182, s[64:65]
	v_add_u32_e32 v182, 0x4000, v182
	global_load_dwordx4 v[168:171], v184, s[0:1]
	v_and_b32_e32 v166, 31, v160
	v_lshrrev_b32_e32 v167, 5, v160
	v_lshl_add_u32 v180, v166, 8, v164
	v_and_b32_e32 v166, 7, v166
	v_xor_b32_e32 v166, v166, v167
	v_lshlrev_b32_e32 v166, 4, v166
	v_add_u32_e32 v172, v180, v166
	v_xor_b32_e32 v167, 0x20, v166
	v_add_u32_e32 v173, v180, v167
	v_xor_b32_e32 v167, 0x40, v166
	v_add_u32_e32 v174, v180, v167
	v_xor_b32_e32 v167, 0x60, v166
	v_add_u32_e32 v175, v180, v167
	v_xor_b32_e32 v167, 0x80, v166
	v_add_u32_e32 v176, v180, v167
	v_xor_b32_e32 v167, 0xa0, v166
	v_add_u32_e32 v177, v180, v167
	v_xor_b32_e32 v167, 0xc0, v166
	v_add_u32_e32 v178, v180, v167
	v_xor_b32_e32 v167, 0xe0, v166
	v_add_u32_e32 v179, v180, v167
	v_lshrrev_b32_e32 v166, 4, v160
	v_and_b32_e32 v167, 15, v160
	v_xor_b32_e32 v167, v166, v167
	v_lshlrev_b32_e32 v167, 4, v167
	v_lshl_add_u32 v180, v166, 8, v164
	v_add_u32_e32 v181, v180, v167
	v_xor_b32_e32 v167, 0x40, v167
	v_add_u32_e32 v166, v180, v167
	v_mov_b32_e32 v180, v181
	v_mov_b32_e32 v181, v166
	ds_write_b128 v172, v[112:115]
	ds_write_b128 v173, v[116:119]
	ds_write_b128 v174, v[120:123]
	ds_write_b128 v175, v[124:127]
	ds_write_b128 v176, v[96:99]
	ds_write_b128 v177, v[100:103]
	ds_write_b128 v178, v[104:107]
	ds_write_b128 v179, v[108:111]
	s_waitcnt lgkmcnt(0)
	ds_read_b128 v[96:99], v180
	ds_read_b128 v[100:103], v181 offset:1024
	ds_read_b128 v[104:107], v180 offset:2048
	ds_read_b128 v[108:111], v181 offset:3072
	ds_read_b128 v[112:115], v180 offset:4096
	ds_read_b128 v[116:119], v181 offset:5120
	ds_read_b128 v[120:123], v180 offset:6144
	ds_read_b128 v[124:127], v181 offset:7168
	s_waitcnt vmcnt(0)
	s_waitcnt lgkmcnt(7)
	v_fma_f32 v96, v168, v96, v128
	v_fma_f32 v97, v169, v97, v129
	v_fma_f32 v98, v170, v98, v130
	v_fma_f32 v99, v171, v99, v131
	global_store_dwordx4 v183, v[96:99], s[64:65]
	v_add_u32_e32 v183, 0x4000, v183
	s_waitcnt lgkmcnt(6)
	v_fma_f32 v100, v168, v100, v132
	v_fma_f32 v101, v169, v101, v133
	v_fma_f32 v102, v170, v102, v134
	v_fma_f32 v103, v171, v103, v135
	global_store_dwordx4 v183, v[100:103], s[64:65]
	v_add_u32_e32 v183, 0x4000, v183
	s_waitcnt lgkmcnt(5)
	v_fma_f32 v104, v168, v104, v136
	v_fma_f32 v105, v169, v105, v137
	v_fma_f32 v106, v170, v106, v138
	v_fma_f32 v107, v171, v107, v139
	global_store_dwordx4 v183, v[104:107], s[64:65]
	v_add_u32_e32 v183, 0x4000, v183
	s_waitcnt lgkmcnt(4)
	v_fma_f32 v108, v168, v108, v140
	v_fma_f32 v109, v169, v109, v141
	v_fma_f32 v110, v170, v110, v142
	v_fma_f32 v111, v171, v111, v143
	global_store_dwordx4 v183, v[108:111], s[64:65]
	v_add_u32_e32 v183, 0x4000, v183
	s_waitcnt lgkmcnt(3)
	v_fma_f32 v112, v168, v112, v144
	v_fma_f32 v113, v169, v113, v145
	v_fma_f32 v114, v170, v114, v146
	v_fma_f32 v115, v171, v115, v147
	global_store_dwordx4 v183, v[112:115], s[64:65]
	v_add_u32_e32 v183, 0x4000, v183
	s_waitcnt lgkmcnt(2)
	v_fma_f32 v116, v168, v116, v148
	v_fma_f32 v117, v169, v117, v149
	v_fma_f32 v118, v170, v118, v150
	v_fma_f32 v119, v171, v119, v151
	global_store_dwordx4 v183, v[116:119], s[64:65]
	v_add_u32_e32 v183, 0x4000, v183
	s_waitcnt lgkmcnt(1)
	v_fma_f32 v120, v168, v120, v152
	v_fma_f32 v121, v169, v121, v153
	v_fma_f32 v122, v170, v122, v154
	v_fma_f32 v123, v171, v123, v155
	global_store_dwordx4 v183, v[120:123], s[64:65]
	v_add_u32_e32 v183, 0x4000, v183
	s_waitcnt lgkmcnt(0)
	v_fma_f32 v124, v168, v124, v156
	v_fma_f32 v125, v169, v125, v157
	v_fma_f32 v126, v170, v126, v158
	v_fma_f32 v127, v171, v127, v159
	global_store_dwordx4 v183, v[124:127], s[64:65]
	v_add_u32_e32 v183, 0x4000, v183
	global_load_dwordx4 v[128:131], v182, s[64:65]
	v_add_u32_e32 v182, 0x4000, v182
	global_load_dwordx4 v[132:135], v182, s[64:65]
	v_add_u32_e32 v182, 0x4000, v182
	global_load_dwordx4 v[136:139], v182, s[64:65]
	v_add_u32_e32 v182, 0x4000, v182
	global_load_dwordx4 v[140:143], v182, s[64:65]
	v_add_u32_e32 v182, 0x4000, v182
	global_load_dwordx4 v[144:147], v182, s[64:65]
	v_add_u32_e32 v182, 0x4000, v182
	global_load_dwordx4 v[148:151], v182, s[64:65]
	v_add_u32_e32 v182, 0x4000, v182
	global_load_dwordx4 v[152:155], v182, s[64:65]
	v_add_u32_e32 v182, 0x4000, v182
	global_load_dwordx4 v[156:159], v182, s[64:65]
	v_add_u32_e32 v182, 0x4000, v182
	ds_write_b128 v172, v[80:83]
	ds_write_b128 v173, v[84:87]
	ds_write_b128 v174, v[88:91]
	ds_write_b128 v175, v[92:95]
	ds_write_b128 v176, v[64:67]
	ds_write_b128 v177, v[68:71]
	ds_write_b128 v178, v[72:75]
	ds_write_b128 v179, v[76:79]
	s_waitcnt lgkmcnt(0)
	ds_read_b128 v[64:67], v180
	ds_read_b128 v[68:71], v181 offset:1024
	ds_read_b128 v[72:75], v180 offset:2048
	ds_read_b128 v[76:79], v181 offset:3072
	ds_read_b128 v[80:83], v180 offset:4096
	ds_read_b128 v[84:87], v181 offset:5120
	ds_read_b128 v[88:91], v180 offset:6144
	ds_read_b128 v[92:95], v181 offset:7168
	s_waitcnt lgkmcnt(7)
	v_fma_f32 v64, v168, v64, v188
	v_fma_f32 v65, v169, v65, v189
	v_fma_f32 v66, v170, v66, v190
	v_fma_f32 v67, v171, v67, v191
	global_store_dwordx4 v183, v[64:67], s[64:65]
	v_add_u32_e32 v183, 0x4000, v183
	s_waitcnt lgkmcnt(6)
; template <class F>
; DEV void acc_foreach(Acc& acc, int m0, int n0, F f) {
;   asm volatile("s_nop 7\n\ts_nop 7\n\ts_nop 3" ::: "memory");
;   const int tid = tidx_full();
;   const int wave = tid >> 6, lane = tid & 63;
;   const int wm = (wave >> 2) * 128, wn = (wave & 3) * 64;
;   const int lr = lane & 31, lh = lane >> 5;
; #pragma unroll
;   for (int i = 0; i < 4; ++i)
; #pragma unroll
;     for (int j = 0; j < 2; ++j)
; #pragma unroll
;       for (int r = 0; r < 16; ++r) {
;         const int m = m0 + wm + 32 * i + (r & 3) + 8 * (r >> 2) + 4 * lh;
;         const int n = n0 + wn + 32 * j + lr;
;         float v = acc[i][j][r];
;         f(m, n, v);
;         acc[i][j][r] = v;
;       }
; }
	v_fma_f32 v68, v168, v68, v192
	v_fma_f32 v69, v169, v69, v193
	v_fma_f32 v70, v170, v70, v194
	v_fma_f32 v71, v171, v71, v195
	global_store_dwordx4 v183, v[68:71], s[64:65]
	v_add_u32_e32 v183, 0x4000, v183
	s_waitcnt lgkmcnt(5)
	v_fma_f32 v72, v168, v72, v196
	v_fma_f32 v73, v169, v73, v197
	v_fma_f32 v74, v170, v74, v198
	v_fma_f32 v75, v171, v75, v199
	global_store_dwordx4 v183, v[72:75], s[64:65]
	v_add_u32_e32 v183, 0x4000, v183
	s_waitcnt lgkmcnt(4)
	v_fma_f32 v76, v168, v76, v222
	v_fma_f32 v77, v169, v77, v223
	v_fma_f32 v78, v170, v78, v224
	v_fma_f32 v79, v171, v79, v225
	global_store_dwordx4 v183, v[76:79], s[64:65]
	v_add_u32_e32 v183, 0x4000, v183
	s_waitcnt lgkmcnt(3)
	v_fma_f32 v80, v168, v80, v226
	v_fma_f32 v81, v169, v81, v227
	v_fma_f32 v82, v170, v82, v228
	v_fma_f32 v83, v171, v83, v229
	global_store_dwordx4 v183, v[80:83], s[64:65]
	v_add_u32_e32 v183, 0x4000, v183
	s_waitcnt lgkmcnt(2)
	v_fma_f32 v84, v168, v84, v230
	v_fma_f32 v85, v169, v85, v231
	v_fma_f32 v86, v170, v86, v232
	v_fma_f32 v87, v171, v87, v233
	global_store_dwordx4 v183, v[84:87], s[64:65]
	v_add_u32_e32 v183, 0x4000, v183
	s_waitcnt lgkmcnt(1)
	v_fma_f32 v88, v168, v88, v234
	v_fma_f32 v89, v169, v89, v235
	v_fma_f32 v90, v170, v90, v236
	v_fma_f32 v91, v171, v91, v237
	global_store_dwordx4 v183, v[88:91], s[64:65]
	v_add_u32_e32 v183, 0x4000, v183
	s_waitcnt lgkmcnt(0)
	v_fma_f32 v92, v168, v92, v238
	v_fma_f32 v93, v169, v93, v239
	v_fma_f32 v94, v170, v94, v240
	v_fma_f32 v95, v171, v95, v241
	global_store_dwordx4 v183, v[92:95], s[64:65]
	v_add_u32_e32 v183, 0x4000, v183
	global_load_dwordx4 v[188:191], v182, s[64:65]
	v_add_u32_e32 v182, 0x4000, v182
	global_load_dwordx4 v[192:195], v182, s[64:65]
	v_add_u32_e32 v182, 0x4000, v182
	global_load_dwordx4 v[196:199], v182, s[64:65]
	v_add_u32_e32 v182, 0x4000, v182
	global_load_dwordx4 v[222:225], v182, s[64:65]
	v_add_u32_e32 v182, 0x4000, v182
	global_load_dwordx4 v[226:229], v182, s[64:65]
	v_add_u32_e32 v182, 0x4000, v182
	global_load_dwordx4 v[230:233], v182, s[64:65]
	v_add_u32_e32 v182, 0x4000, v182
	global_load_dwordx4 v[234:237], v182, s[64:65]
	v_add_u32_e32 v182, 0x4000, v182
	global_load_dwordx4 v[238:241], v182, s[64:65]
	v_add_u32_e32 v182, 0x4000, v182
	ds_write_b128 v172, v[48:51]
	ds_write_b128 v173, v[52:55]
	ds_write_b128 v174, v[56:59]
	ds_write_b128 v175, v[60:63]
	ds_write_b128 v176, v[32:35]
	ds_write_b128 v177, v[36:39]
	ds_write_b128 v178, v[40:43]
	ds_write_b128 v179, v[44:47]
	s_waitcnt lgkmcnt(0)
	ds_read_b128 v[32:35], v180
	ds_read_b128 v[36:39], v181 offset:1024
	ds_read_b128 v[40:43], v180 offset:2048
	ds_read_b128 v[44:47], v181 offset:3072
	ds_read_b128 v[48:51], v180 offset:4096
	ds_read_b128 v[52:55], v181 offset:5120
	ds_read_b128 v[56:59], v180 offset:6144
	ds_read_b128 v[60:63], v181 offset:7168
	s_waitcnt vmcnt(16)
	s_waitcnt lgkmcnt(7)
	v_fma_f32 v32, v168, v32, v128
	v_fma_f32 v33, v169, v33, v129
	v_fma_f32 v34, v170, v34, v130
	v_fma_f32 v35, v171, v35, v131
	global_store_dwordx4 v183, v[32:35], s[64:65]
	v_add_u32_e32 v183, 0x4000, v183
	s_waitcnt lgkmcnt(6)
	v_fma_f32 v36, v168, v36, v132
	v_fma_f32 v37, v169, v37, v133
	v_fma_f32 v38, v170, v38, v134
	v_fma_f32 v39, v171, v39, v135
	global_store_dwordx4 v183, v[36:39], s[64:65]
	v_add_u32_e32 v183, 0x4000, v183
	s_waitcnt lgkmcnt(5)
	v_fma_f32 v40, v168, v40, v136
	v_fma_f32 v41, v169, v41, v137
	v_fma_f32 v42, v170, v42, v138
	v_fma_f32 v43, v171, v43, v139
	global_store_dwordx4 v183, v[40:43], s[64:65]
	v_add_u32_e32 v183, 0x4000, v183
	s_waitcnt lgkmcnt(4)
; template <class F>
; DEV void acc_foreach(Acc& acc, int m0, int n0, F f) {
;   asm volatile("s_nop 7\n\ts_nop 7\n\ts_nop 3" ::: "memory");
;   const int tid = tidx_full();
;   const int wave = tid >> 6, lane = tid & 63;
;   const int wm = (wave >> 2) * 128, wn = (wave & 3) * 64;
;   const int lr = lane & 31, lh = lane >> 5;
; #pragma unroll
;   for (int i = 0; i < 4; ++i)
; #pragma unroll
;     for (int j = 0; j < 2; ++j)
; #pragma unroll
;       for (int r = 0; r < 16; ++r) {
;         const int m = m0 + wm + 32 * i + (r & 3) + 8 * (r >> 2) + 4 * lh;
;         const int n = n0 + wn + 32 * j + lr;
;         float v = acc[i][j][r];
;         f(m, n, v);
;         acc[i][j][r] = v;
;       }
; }
; DEV void phase_ff2(const Params& p, int g, char* smem) {
;     ...
;   for (int iter = 0;; ++iter) {
;     int mt, nt;
;     if (!tile_map(iter, 128, 4, mt, nt)) break;
	v_fma_f32 v44, v168, v44, v140
	v_fma_f32 v45, v169, v45, v141
	v_fma_f32 v46, v170, v46, v142
	v_fma_f32 v47, v171, v47, v143
	global_store_dwordx4 v183, v[44:47], s[64:65]
	v_add_u32_e32 v183, 0x4000, v183
	s_waitcnt lgkmcnt(3)
	v_fma_f32 v48, v168, v48, v144
	v_fma_f32 v49, v169, v49, v145
	v_fma_f32 v50, v170, v50, v146
	v_fma_f32 v51, v171, v51, v147
	global_store_dwordx4 v183, v[48:51], s[64:65]
	v_add_u32_e32 v183, 0x4000, v183
	s_waitcnt lgkmcnt(2)
	v_fma_f32 v52, v168, v52, v148
	v_fma_f32 v53, v169, v53, v149
	v_fma_f32 v54, v170, v54, v150
	v_fma_f32 v55, v171, v55, v151
	global_store_dwordx4 v183, v[52:55], s[64:65]
	v_add_u32_e32 v183, 0x4000, v183
	s_waitcnt lgkmcnt(1)
	v_fma_f32 v56, v168, v56, v152
	v_fma_f32 v57, v169, v57, v153
	v_fma_f32 v58, v170, v58, v154
	v_fma_f32 v59, v171, v59, v155
	global_store_dwordx4 v183, v[56:59], s[64:65]
	v_add_u32_e32 v183, 0x4000, v183
	s_waitcnt lgkmcnt(0)
	v_fma_f32 v60, v168, v60, v156
	v_fma_f32 v61, v169, v61, v157
	v_fma_f32 v62, v170, v62, v158
	v_fma_f32 v63, v171, v63, v159
	global_store_dwordx4 v183, v[60:63], s[64:65]
	v_add_u32_e32 v183, 0x4000, v183
	ds_write_b128 v172, v[16:19]
	ds_write_b128 v173, v[20:23]
	ds_write_b128 v174, v[24:27]
	ds_write_b128 v175, v[28:31]
	ds_write_b128 v176, v[0:3]
	ds_write_b128 v177, v[4:7]
	ds_write_b128 v178, v[8:11]
	ds_write_b128 v179, v[12:15]
	s_waitcnt lgkmcnt(0)
	ds_read_b128 v[0:3], v180
	ds_read_b128 v[4:7], v181 offset:1024
	ds_read_b128 v[8:11], v180 offset:2048
	ds_read_b128 v[12:15], v181 offset:3072
	ds_read_b128 v[16:19], v180 offset:4096
	ds_read_b128 v[20:23], v181 offset:5120
	ds_read_b128 v[24:27], v180 offset:6144
	ds_read_b128 v[28:31], v181 offset:7168
	s_waitcnt vmcnt(8)
	s_waitcnt lgkmcnt(7)
	v_fma_f32 v0, v168, v0, v188
	v_fma_f32 v1, v169, v1, v189
	v_fma_f32 v2, v170, v2, v190
	v_fma_f32 v3, v171, v3, v191
	global_store_dwordx4 v183, v[0:3], s[64:65]
	v_add_u32_e32 v183, 0x4000, v183
	s_waitcnt lgkmcnt(6)
	v_fma_f32 v4, v168, v4, v192
	v_fma_f32 v5, v169, v5, v193
	v_fma_f32 v6, v170, v6, v194
	v_fma_f32 v7, v171, v7, v195
	global_store_dwordx4 v183, v[4:7], s[64:65]
	v_add_u32_e32 v183, 0x4000, v183
	s_waitcnt lgkmcnt(5)
	v_fma_f32 v8, v168, v8, v196
	v_fma_f32 v9, v169, v9, v197
	v_fma_f32 v10, v170, v10, v198
	v_fma_f32 v11, v171, v11, v199
	global_store_dwordx4 v183, v[8:11], s[64:65]
	v_add_u32_e32 v183, 0x4000, v183
	s_waitcnt lgkmcnt(4)
	v_fma_f32 v12, v168, v12, v222
	v_fma_f32 v13, v169, v13, v223
	v_fma_f32 v14, v170, v14, v224
	v_fma_f32 v15, v171, v15, v225
	global_store_dwordx4 v183, v[12:15], s[64:65]
	v_add_u32_e32 v183, 0x4000, v183
	s_waitcnt lgkmcnt(3)
	v_fma_f32 v16, v168, v16, v226
	v_fma_f32 v17, v169, v17, v227
	v_fma_f32 v18, v170, v18, v228
	v_fma_f32 v19, v171, v19, v229
	global_store_dwordx4 v183, v[16:19], s[64:65]
	v_add_u32_e32 v183, 0x4000, v183
	s_waitcnt lgkmcnt(2)
	v_fma_f32 v20, v168, v20, v230
	v_fma_f32 v21, v169, v21, v231
	v_fma_f32 v22, v170, v22, v232
	v_fma_f32 v23, v171, v23, v233
	global_store_dwordx4 v183, v[20:23], s[64:65]
	v_add_u32_e32 v183, 0x4000, v183
	s_waitcnt lgkmcnt(1)
	v_fma_f32 v24, v168, v24, v234
	v_fma_f32 v25, v169, v25, v235
	v_fma_f32 v26, v170, v26, v236
	v_fma_f32 v27, v171, v27, v237
	global_store_dwordx4 v183, v[24:27], s[64:65]
	v_add_u32_e32 v183, 0x4000, v183
	s_waitcnt lgkmcnt(0)
	v_fma_f32 v28, v168, v28, v238
	v_fma_f32 v29, v169, v29, v239
	v_fma_f32 v30, v170, v30, v240
	v_fma_f32 v31, v171, v31, v241
	global_store_dwordx4 v183, v[28:31], s[64:65]
	v_add_u32_e32 v183, 0x4000, v183
	s_add_i32 s4, s4, 1
	s_mov_b64 s[2:3], 0
	s_branch .LBB0_1182
